# v40 + removed redundant lgkmcnt(0) after barrier+setprio in GEMM K-loops
# baseline (speedup 1.0000x reference)
.LBB0_194:
	s_add_u32 s24, s22, 0xfffc0080
	s_addc_u32 s25, s23, -1
	s_add_i32 s55, 0, 0x10000
	s_cmp_eq_u32 s54, 12
	s_cselect_b32 s27, s15, s25
	s_cselect_b32 s26, s46, s24
	v_add_u32_e32 v140, s55, v143
	s_cselect_b32 s25, s13, s53
	s_cselect_b32 s24, s47, s52
	s_add_i32 s69, 0, 0x14000
	ds_read_b128 v[162:165], v140
	ds_read_b128 v[166:169], v140 offset:1024
	ds_read_b128 v[170:173], v140 offset:2048
	ds_read_b128 v[174:177], v140 offset:3072
	v_add_u32_e32 v140, s69, v143
	ds_read_b128 v[178:181], v140
	ds_read_b128 v[182:185], v140 offset:1024
	ds_read_b128 v[186:189], v140 offset:2048
	ds_read_b128 v[190:193], v140 offset:3072
	v_lshl_add_u64 v[140:141], s[22:23], 0, v[136:137]
	s_add_i32 m0, s38, 0xc000
	ds_read_b128 v[194:197], v145
	ds_read_b128 v[198:201], v145 offset:1024
	ds_read_b128 v[202:205], v145 offset:2048
	ds_read_b128 v[206:209], v145 offset:3072
	ds_read_b128 v[232:235], v145 offset:4096
	ds_read_b128 v[236:239], v145 offset:5120
	ds_read_b128 v[240:243], v145 offset:6144
	ds_read_b128 v[244:247], v145 offset:7168
	global_load_lds_dwordx4 v[140:141], off
	v_lshl_add_u64 v[140:141], s[22:23], 0, v[138:139]
	s_add_i32 m0, s38, 0xe000
	s_nop 0
	global_load_lds_dwordx4 v[140:141], off
	s_waitcnt vmcnt(8)
	s_waitcnt lgkmcnt(0)
	s_barrier
	s_setprio 1
	v_mfma_f32_16x16x32_bf16 v[126:129], v[162:165], v[194:197], v[126:129]
	v_mfma_f32_16x16x32_bf16 v[118:121], v[170:173], v[194:197], v[118:121]
	v_mfma_f32_16x16x32_bf16 v[110:113], v[162:165], v[202:205], v[110:113]
	v_mfma_f32_16x16x32_bf16 v[102:105], v[170:173], v[202:205], v[102:105]
	v_mfma_f32_16x16x32_bf16 v[94:97], v[162:165], v[232:235], v[94:97]
	v_mfma_f32_16x16x32_bf16 v[86:89], v[170:173], v[232:235], v[86:89]
	v_mfma_f32_16x16x32_bf16 v[78:81], v[162:165], v[240:243], v[78:81]
	v_mfma_f32_16x16x32_bf16 v[70:73], v[170:173], v[240:243], v[70:73]
	v_mfma_f32_16x16x32_bf16 v[126:129], v[166:169], v[198:201], v[126:129]
	v_mfma_f32_16x16x32_bf16 v[118:121], v[174:177], v[198:201], v[118:121]
	v_mfma_f32_16x16x32_bf16 v[110:113], v[166:169], v[206:209], v[110:113]
	v_mfma_f32_16x16x32_bf16 v[102:105], v[174:177], v[206:209], v[102:105]
	v_mfma_f32_16x16x32_bf16 v[94:97], v[166:169], v[236:239], v[94:97]
	v_mfma_f32_16x16x32_bf16 v[86:89], v[174:177], v[236:239], v[86:89]
	v_mfma_f32_16x16x32_bf16 v[78:81], v[166:169], v[244:247], v[78:81]
	v_mfma_f32_16x16x32_bf16 v[70:73], v[174:177], v[244:247], v[70:73]
	v_mfma_f32_16x16x32_bf16 v[122:125], v[178:181], v[194:197], v[122:125]
	v_mfma_f32_16x16x32_bf16 v[114:117], v[186:189], v[194:197], v[114:117]
	v_mfma_f32_16x16x32_bf16 v[106:109], v[178:181], v[202:205], v[106:109]
	v_mfma_f32_16x16x32_bf16 v[98:101], v[186:189], v[202:205], v[98:101]
	v_mfma_f32_16x16x32_bf16 v[90:93], v[178:181], v[232:235], v[90:93]
	v_mfma_f32_16x16x32_bf16 v[82:85], v[186:189], v[232:235], v[82:85]
	v_mfma_f32_16x16x32_bf16 v[74:77], v[178:181], v[240:243], v[74:77]
	v_mfma_f32_16x16x32_bf16 v[66:69], v[186:189], v[240:243], v[66:69]
	v_mfma_f32_16x16x32_bf16 v[122:125], v[182:185], v[198:201], v[122:125]
	v_mfma_f32_16x16x32_bf16 v[114:117], v[190:193], v[198:201], v[114:117]
	v_mfma_f32_16x16x32_bf16 v[106:109], v[182:185], v[206:209], v[106:109]
	v_mfma_f32_16x16x32_bf16 v[98:101], v[190:193], v[206:209], v[98:101]
	v_mfma_f32_16x16x32_bf16 v[90:93], v[182:185], v[236:239], v[90:93]
	v_mfma_f32_16x16x32_bf16 v[82:85], v[190:193], v[236:239], v[82:85]
	v_mfma_f32_16x16x32_bf16 v[74:77], v[182:185], v[244:247], v[74:77]
	v_mfma_f32_16x16x32_bf16 v[66:69], v[190:193], v[244:247], v[66:69]
	s_setprio 0
	s_barrier
	s_add_i32 s55, s55, s36
	v_lshl_add_u64 v[140:141], s[24:25], 0, v[0:1]
	s_mov_b32 m0, s55
	ds_read_b128 v[194:197], v145 offset:16384
	ds_read_b128 v[198:201], v145 offset:17408
	ds_read_b128 v[202:205], v145 offset:18432
	ds_read_b128 v[206:209], v145 offset:19456
	ds_read_b128 v[232:235], v145 offset:20480
	ds_read_b128 v[236:239], v145 offset:21504
	ds_read_b128 v[240:243], v145 offset:22528
	ds_read_b128 v[244:247], v145 offset:23552
	global_load_lds_dwordx4 v[140:141], off
	s_add_i32 m0, s55, 0x2000
	s_add_u32 s56, s24, 0x40000
	v_lshl_add_u64 v[210:211], s[24:25], 0, v[130:131]
	s_addc_u32 s57, s25, 0
	s_add_i32 s55, s69, s36
	global_load_lds_dwordx4 v[210:211], off
	v_lshl_add_u64 v[220:221], s[56:57], 0, v[0:1]
	s_mov_b32 m0, s55
	v_lshl_add_u64 v[222:223], s[26:27], 0, v[132:133]
	global_load_lds_dwordx4 v[220:221], off
	v_lshl_add_u64 v[220:221], s[56:57], 0, v[130:131]
	s_add_i32 m0, s55, 0x2000
	s_nop 0
	global_load_lds_dwordx4 v[220:221], off
	v_lshl_add_u64 v[220:221], s[26:27], 0, v[134:135]
	s_mov_b32 m0, s38
	s_nop 0
	global_load_lds_dwordx4 v[220:221], off
	s_mov_b32 m0, s39
	s_nop 0
	global_load_lds_dwordx4 v[222:223], off
	s_waitcnt vmcnt(8)
	s_waitcnt lgkmcnt(0)
	s_barrier
	s_setprio 1
	v_mfma_f32_16x16x32_bf16 v[62:65], v[162:165], v[194:197], v[62:65]
	v_mfma_f32_16x16x32_bf16 v[54:57], v[170:173], v[194:197], v[54:57]
	v_mfma_f32_16x16x32_bf16 v[46:49], v[162:165], v[202:205], v[46:49]
	v_mfma_f32_16x16x32_bf16 v[38:41], v[170:173], v[202:205], v[38:41]
	v_mfma_f32_16x16x32_bf16 v[30:33], v[162:165], v[232:235], v[30:33]
	v_mfma_f32_16x16x32_bf16 v[22:25], v[170:173], v[232:235], v[22:25]
	v_mfma_f32_16x16x32_bf16 v[14:17], v[162:165], v[240:243], v[14:17]
	v_mfma_f32_16x16x32_bf16 v[6:9], v[170:173], v[240:243], v[6:9]
	v_mfma_f32_16x16x32_bf16 v[62:65], v[166:169], v[198:201], v[62:65]
	v_mfma_f32_16x16x32_bf16 v[54:57], v[174:177], v[198:201], v[54:57]
	v_mfma_f32_16x16x32_bf16 v[46:49], v[166:169], v[206:209], v[46:49]
	v_mfma_f32_16x16x32_bf16 v[38:41], v[174:177], v[206:209], v[38:41]
	v_mfma_f32_16x16x32_bf16 v[30:33], v[166:169], v[236:239], v[30:33]
	v_mfma_f32_16x16x32_bf16 v[22:25], v[174:177], v[236:239], v[22:25]
	v_mfma_f32_16x16x32_bf16 v[14:17], v[166:169], v[244:247], v[14:17]
	v_mfma_f32_16x16x32_bf16 v[6:9], v[174:177], v[244:247], v[6:9]
	v_mfma_f32_16x16x32_bf16 v[58:61], v[178:181], v[194:197], v[58:61]
	v_mfma_f32_16x16x32_bf16 v[50:53], v[186:189], v[194:197], v[50:53]
	v_mfma_f32_16x16x32_bf16 v[42:45], v[178:181], v[202:205], v[42:45]
	v_mfma_f32_16x16x32_bf16 v[34:37], v[186:189], v[202:205], v[34:37]
	v_mfma_f32_16x16x32_bf16 v[26:29], v[178:181], v[232:235], v[26:29]
	v_mfma_f32_16x16x32_bf16 v[18:21], v[186:189], v[232:235], v[18:21]
	v_mfma_f32_16x16x32_bf16 v[10:13], v[178:181], v[240:243], v[10:13]
	v_mfma_f32_16x16x32_bf16 v[2:5], v[186:189], v[240:243], v[2:5]
	v_mfma_f32_16x16x32_bf16 v[58:61], v[182:185], v[198:201], v[58:61]
	v_mfma_f32_16x16x32_bf16 v[50:53], v[190:193], v[198:201], v[50:53]
	v_mfma_f32_16x16x32_bf16 v[42:45], v[182:185], v[206:209], v[42:45]
	v_mfma_f32_16x16x32_bf16 v[34:37], v[190:193], v[206:209], v[34:37]
	v_mfma_f32_16x16x32_bf16 v[26:29], v[182:185], v[236:239], v[26:29]
	v_mfma_f32_16x16x32_bf16 v[18:21], v[190:193], v[236:239], v[18:21]
	v_mfma_f32_16x16x32_bf16 v[10:13], v[182:185], v[244:247], v[10:13]
	v_mfma_f32_16x16x32_bf16 v[2:5], v[190:193], v[244:247], v[2:5]
	s_setprio 0
	s_barrier
	s_add_i32 s55, 0, 0x18000
	v_add_u32_e32 v146, s55, v143
	s_add_i32 s56, 0, 0x1c000
	ds_read_b128 v[162:165], v146
	ds_read_b128 v[166:169], v146 offset:1024
	ds_read_b128 v[170:173], v146 offset:2048
	ds_read_b128 v[174:177], v146 offset:3072
	v_add_u32_e32 v146, s56, v143
	ds_read_b128 v[178:181], v146
	ds_read_b128 v[182:185], v146 offset:1024
	ds_read_b128 v[186:189], v146 offset:2048
	ds_read_b128 v[190:193], v146 offset:3072
	s_add_u32 s26, s26, 0x40000
	s_addc_u32 s27, s27, 0
	s_mov_b32 m0, s40
	v_lshl_add_u64 v[248:249], s[26:27], 0, v[134:135]
	ds_read_b128 v[194:197], v145 offset:32768
	ds_read_b128 v[198:201], v145 offset:33792
	ds_read_b128 v[202:205], v145 offset:34816
	ds_read_b128 v[206:209], v145 offset:35840
	ds_read_b128 v[232:235], v145 offset:36864
	ds_read_b128 v[236:239], v145 offset:37888
	ds_read_b128 v[240:243], v145 offset:38912
	ds_read_b128 v[244:247], v145 offset:39936
	global_load_lds_dwordx4 v[248:249], off
	v_lshl_add_u64 v[248:249], s[26:27], 0, v[132:133]
	s_mov_b32 m0, s41
	s_nop 0
	global_load_lds_dwordx4 v[248:249], off
	s_waitcnt vmcnt(8)
	s_waitcnt lgkmcnt(0)
	s_barrier
	s_setprio 1
	v_mfma_f32_16x16x32_bf16 v[126:129], v[162:165], v[194:197], v[126:129]
	v_mfma_f32_16x16x32_bf16 v[118:121], v[170:173], v[194:197], v[118:121]
	v_mfma_f32_16x16x32_bf16 v[110:113], v[162:165], v[202:205], v[110:113]
	v_mfma_f32_16x16x32_bf16 v[102:105], v[170:173], v[202:205], v[102:105]
	v_mfma_f32_16x16x32_bf16 v[94:97], v[162:165], v[232:235], v[94:97]
	v_mfma_f32_16x16x32_bf16 v[86:89], v[170:173], v[232:235], v[86:89]
	v_mfma_f32_16x16x32_bf16 v[78:81], v[162:165], v[240:243], v[78:81]
	v_mfma_f32_16x16x32_bf16 v[70:73], v[170:173], v[240:243], v[70:73]
	v_mfma_f32_16x16x32_bf16 v[126:129], v[166:169], v[198:201], v[126:129]
	v_mfma_f32_16x16x32_bf16 v[118:121], v[174:177], v[198:201], v[118:121]
	v_mfma_f32_16x16x32_bf16 v[110:113], v[166:169], v[206:209], v[110:113]
	v_mfma_f32_16x16x32_bf16 v[102:105], v[174:177], v[206:209], v[102:105]
	v_mfma_f32_16x16x32_bf16 v[94:97], v[166:169], v[236:239], v[94:97]
	v_mfma_f32_16x16x32_bf16 v[86:89], v[174:177], v[236:239], v[86:89]
	v_mfma_f32_16x16x32_bf16 v[78:81], v[166:169], v[244:247], v[78:81]
	v_mfma_f32_16x16x32_bf16 v[70:73], v[174:177], v[244:247], v[70:73]
	v_mfma_f32_16x16x32_bf16 v[122:125], v[178:181], v[194:197], v[122:125]
	v_mfma_f32_16x16x32_bf16 v[114:117], v[186:189], v[194:197], v[114:117]
	v_mfma_f32_16x16x32_bf16 v[106:109], v[178:181], v[202:205], v[106:109]
	v_mfma_f32_16x16x32_bf16 v[98:101], v[186:189], v[202:205], v[98:101]
	v_mfma_f32_16x16x32_bf16 v[90:93], v[178:181], v[232:235], v[90:93]
	v_mfma_f32_16x16x32_bf16 v[82:85], v[186:189], v[232:235], v[82:85]
	v_mfma_f32_16x16x32_bf16 v[74:77], v[178:181], v[240:243], v[74:77]
	v_mfma_f32_16x16x32_bf16 v[66:69], v[186:189], v[240:243], v[66:69]
	v_mfma_f32_16x16x32_bf16 v[122:125], v[182:185], v[198:201], v[122:125]
	v_mfma_f32_16x16x32_bf16 v[114:117], v[190:193], v[198:201], v[114:117]
	v_mfma_f32_16x16x32_bf16 v[106:109], v[182:185], v[206:209], v[106:109]
	v_mfma_f32_16x16x32_bf16 v[98:101], v[190:193], v[206:209], v[98:101]
	v_mfma_f32_16x16x32_bf16 v[90:93], v[182:185], v[236:239], v[90:93]
	v_mfma_f32_16x16x32_bf16 v[82:85], v[190:193], v[236:239], v[82:85]
	v_mfma_f32_16x16x32_bf16 v[74:77], v[182:185], v[244:247], v[74:77]
	v_mfma_f32_16x16x32_bf16 v[66:69], v[190:193], v[244:247], v[66:69]
	s_setprio 0
	s_barrier
	s_add_i32 s26, s55, s36
	v_lshl_add_u64 v[140:141], v[140:141], 0, s[90:91]
	s_mov_b32 m0, s26
	ds_read_b128 v[194:197], v145 offset:49152
	ds_read_b128 v[198:201], v145 offset:50176
	ds_read_b128 v[202:205], v145 offset:51200
	ds_read_b128 v[206:209], v145 offset:52224
	ds_read_b128 v[232:235], v145 offset:53248
	ds_read_b128 v[236:239], v145 offset:54272
	ds_read_b128 v[240:243], v145 offset:55296
	ds_read_b128 v[244:247], v145 offset:56320
	global_load_lds_dwordx4 v[140:141], off
	s_add_i32 m0, s26, 0x2000
	s_add_u32 s24, s24, 0x40080
	v_lshl_add_u64 v[140:141], v[210:211], 0, s[90:91]
	s_addc_u32 s25, s25, 0
	s_add_i32 s26, s56, s36
	global_load_lds_dwordx4 v[140:141], off
	v_lshl_add_u64 v[140:141], s[24:25], 0, v[0:1]
	s_mov_b32 m0, s26
	s_nop 0
	global_load_lds_dwordx4 v[140:141], off
	v_lshl_add_u64 v[140:141], s[24:25], 0, v[130:131]
	s_add_i32 m0, s26, 0x2000
	s_nop 0
	global_load_lds_dwordx4 v[140:141], off
	v_lshl_add_u64 v[140:141], v[220:221], 0, s[90:91]
	s_mov_b32 m0, s42
	s_nop 0
	global_load_lds_dwordx4 v[140:141], off
	v_lshl_add_u64 v[140:141], v[222:223], 0, s[90:91]
	s_mov_b32 m0, s43
	s_nop 0
	global_load_lds_dwordx4 v[140:141], off
	s_waitcnt vmcnt(8)
	s_waitcnt lgkmcnt(0)
	s_barrier
	s_setprio 1
	v_mfma_f32_16x16x32_bf16 v[62:65], v[162:165], v[194:197], v[62:65]
	v_mfma_f32_16x16x32_bf16 v[54:57], v[170:173], v[194:197], v[54:57]
	v_mfma_f32_16x16x32_bf16 v[46:49], v[162:165], v[202:205], v[46:49]
	v_mfma_f32_16x16x32_bf16 v[38:41], v[170:173], v[202:205], v[38:41]
	v_mfma_f32_16x16x32_bf16 v[30:33], v[162:165], v[232:235], v[30:33]
	v_mfma_f32_16x16x32_bf16 v[22:25], v[170:173], v[232:235], v[22:25]
	v_mfma_f32_16x16x32_bf16 v[14:17], v[162:165], v[240:243], v[14:17]
	v_mfma_f32_16x16x32_bf16 v[6:9], v[170:173], v[240:243], v[6:9]
	v_mfma_f32_16x16x32_bf16 v[62:65], v[166:169], v[198:201], v[62:65]
	v_mfma_f32_16x16x32_bf16 v[54:57], v[174:177], v[198:201], v[54:57]
	v_mfma_f32_16x16x32_bf16 v[46:49], v[166:169], v[206:209], v[46:49]
	v_mfma_f32_16x16x32_bf16 v[38:41], v[174:177], v[206:209], v[38:41]
	v_mfma_f32_16x16x32_bf16 v[30:33], v[166:169], v[236:239], v[30:33]
	v_mfma_f32_16x16x32_bf16 v[22:25], v[174:177], v[236:239], v[22:25]
	v_mfma_f32_16x16x32_bf16 v[14:17], v[166:169], v[244:247], v[14:17]
	v_mfma_f32_16x16x32_bf16 v[6:9], v[174:177], v[244:247], v[6:9]
	v_mfma_f32_16x16x32_bf16 v[58:61], v[178:181], v[194:197], v[58:61]
	v_mfma_f32_16x16x32_bf16 v[50:53], v[186:189], v[194:197], v[50:53]
	v_mfma_f32_16x16x32_bf16 v[42:45], v[178:181], v[202:205], v[42:45]
	v_mfma_f32_16x16x32_bf16 v[34:37], v[186:189], v[202:205], v[34:37]
	v_mfma_f32_16x16x32_bf16 v[26:29], v[178:181], v[232:235], v[26:29]
	v_mfma_f32_16x16x32_bf16 v[18:21], v[186:189], v[232:235], v[18:21]
	v_mfma_f32_16x16x32_bf16 v[10:13], v[178:181], v[240:243], v[10:13]
	v_mfma_f32_16x16x32_bf16 v[2:5], v[186:189], v[240:243], v[2:5]
	v_mfma_f32_16x16x32_bf16 v[58:61], v[182:185], v[198:201], v[58:61]
	v_mfma_f32_16x16x32_bf16 v[50:53], v[190:193], v[198:201], v[50:53]
	v_mfma_f32_16x16x32_bf16 v[42:45], v[182:185], v[206:209], v[42:45]
	v_mfma_f32_16x16x32_bf16 v[34:37], v[190:193], v[206:209], v[34:37]
	v_mfma_f32_16x16x32_bf16 v[26:29], v[182:185], v[236:239], v[26:29]
	v_mfma_f32_16x16x32_bf16 v[18:21], v[190:193], v[236:239], v[18:21]
	v_mfma_f32_16x16x32_bf16 v[10:13], v[182:185], v[244:247], v[10:13]
	v_mfma_f32_16x16x32_bf16 v[2:5], v[190:193], v[244:247], v[2:5]
	s_setprio 0
	s_barrier
	s_add_i32 s54, s54, 2
	s_add_u32 s22, s22, 0x100
	s_addc_u32 s23, s23, 0
	s_add_u32 s52, s52, 0x100
	s_addc_u32 s53, s53, 0
	s_cmp_gt_u32 s54, 13
	s_cbranch_scc0 .LBB0_194
	s_and_b64 vcc, exec, s[10:11]
	s_cbranch_vccz .LBB0_197
	s_barrier

.LBB0_274:
	s_add_u32 s16, s14, 0x100
	s_addc_u32 s17, s15, 0
	s_add_i32 s47, 0, 0x10000
	s_cmp_eq_u32 s46, 40
	s_cselect_b32 s21, s7, s17
	s_cselect_b32 s20, s6, s16
	v_add_u32_e32 v140, s47, v143
	s_cselect_b32 s19, s13, s45
	s_cselect_b32 s18, s12, s44
	s_add_i32 s52, 0, 0x14000
	ds_read_b128 v[136:139], v140
	ds_read_b128 v[162:165], v140 offset:1024
	ds_read_b128 v[166:169], v140 offset:2048
	ds_read_b128 v[170:173], v140 offset:3072
	v_add_u32_e32 v140, s52, v143
	ds_read_b128 v[174:177], v140
	ds_read_b128 v[178:181], v140 offset:1024
	ds_read_b128 v[182:185], v140 offset:2048
	ds_read_b128 v[186:189], v140 offset:3072
	v_lshl_add_u64 v[140:141], s[14:15], 0, v[132:133]
	s_add_i32 m0, s30, 0xc000
	ds_read_b128 v[190:193], v145
	ds_read_b128 v[194:197], v145 offset:1024
	ds_read_b128 v[198:201], v145 offset:2048
	ds_read_b128 v[202:205], v145 offset:3072
	ds_read_b128 v[206:209], v145 offset:4096
	ds_read_b128 v[232:235], v145 offset:5120
	ds_read_b128 v[236:239], v145 offset:6144
	ds_read_b128 v[240:243], v145 offset:7168
	global_load_lds_dwordx4 v[140:141], off
	v_lshl_add_u64 v[140:141], s[14:15], 0, v[134:135]
	s_add_i32 m0, s30, 0xe000
	s_nop 0
	global_load_lds_dwordx4 v[140:141], off
	s_waitcnt vmcnt(8)
	s_waitcnt lgkmcnt(0)
	s_barrier
	s_setprio 1
	v_mfma_f32_16x16x32_bf16 v[126:129], v[136:139], v[190:193], v[126:129]
	v_mfma_f32_16x16x32_bf16 v[122:125], v[166:169], v[190:193], v[122:125]
	v_mfma_f32_16x16x32_bf16 v[110:113], v[136:139], v[198:201], v[110:113]
	v_mfma_f32_16x16x32_bf16 v[106:109], v[166:169], v[198:201], v[106:109]
	v_mfma_f32_16x16x32_bf16 v[94:97], v[136:139], v[206:209], v[94:97]
	v_mfma_f32_16x16x32_bf16 v[90:93], v[166:169], v[206:209], v[90:93]
	v_mfma_f32_16x16x32_bf16 v[78:81], v[136:139], v[236:239], v[78:81]
	v_mfma_f32_16x16x32_bf16 v[74:77], v[166:169], v[236:239], v[74:77]
	v_mfma_f32_16x16x32_bf16 v[126:129], v[162:165], v[194:197], v[126:129]
	v_mfma_f32_16x16x32_bf16 v[122:125], v[170:173], v[194:197], v[122:125]
	v_mfma_f32_16x16x32_bf16 v[110:113], v[162:165], v[202:205], v[110:113]
	v_mfma_f32_16x16x32_bf16 v[106:109], v[170:173], v[202:205], v[106:109]
	v_mfma_f32_16x16x32_bf16 v[94:97], v[162:165], v[232:235], v[94:97]
	v_mfma_f32_16x16x32_bf16 v[90:93], v[170:173], v[232:235], v[90:93]
	v_mfma_f32_16x16x32_bf16 v[78:81], v[162:165], v[240:243], v[78:81]
	v_mfma_f32_16x16x32_bf16 v[74:77], v[170:173], v[240:243], v[74:77]
	v_mfma_f32_16x16x32_bf16 v[118:121], v[174:177], v[190:193], v[118:121]
	v_mfma_f32_16x16x32_bf16 v[114:117], v[182:185], v[190:193], v[114:117]
	v_mfma_f32_16x16x32_bf16 v[102:105], v[174:177], v[198:201], v[102:105]
	v_mfma_f32_16x16x32_bf16 v[98:101], v[182:185], v[198:201], v[98:101]
	v_mfma_f32_16x16x32_bf16 v[86:89], v[174:177], v[206:209], v[86:89]
	v_mfma_f32_16x16x32_bf16 v[82:85], v[182:185], v[206:209], v[82:85]
	v_mfma_f32_16x16x32_bf16 v[70:73], v[174:177], v[236:239], v[70:73]
	v_mfma_f32_16x16x32_bf16 v[66:69], v[182:185], v[236:239], v[66:69]
	v_mfma_f32_16x16x32_bf16 v[118:121], v[178:181], v[194:197], v[118:121]
	v_mfma_f32_16x16x32_bf16 v[114:117], v[186:189], v[194:197], v[114:117]
	v_mfma_f32_16x16x32_bf16 v[102:105], v[178:181], v[202:205], v[102:105]
	v_mfma_f32_16x16x32_bf16 v[98:101], v[186:189], v[202:205], v[98:101]
	v_mfma_f32_16x16x32_bf16 v[86:89], v[178:181], v[232:235], v[86:89]
	v_mfma_f32_16x16x32_bf16 v[82:85], v[186:189], v[232:235], v[82:85]
	v_mfma_f32_16x16x32_bf16 v[70:73], v[178:181], v[240:243], v[70:73]
	v_mfma_f32_16x16x32_bf16 v[66:69], v[186:189], v[240:243], v[66:69]
	s_setprio 0
	s_barrier
	s_add_i32 s14, s47, s29
	v_lshl_add_u64 v[140:141], s[18:19], 0, v[0:1]
	s_mov_b32 m0, s14
	ds_read_b128 v[190:193], v145 offset:16384
	ds_read_b128 v[194:197], v145 offset:17408
	ds_read_b128 v[198:201], v145 offset:18432
	ds_read_b128 v[202:205], v145 offset:19456
	ds_read_b128 v[206:209], v145 offset:20480
	ds_read_b128 v[232:235], v145 offset:21504
	ds_read_b128 v[236:239], v145 offset:22528
	ds_read_b128 v[240:243], v145 offset:23552
	global_load_lds_dwordx4 v[140:141], off
	s_add_i32 m0, s14, 0x2000
	s_add_u32 s14, s18, 0xb0000
	v_lshl_add_u64 v[210:211], s[18:19], 0, v[130:131]
	s_addc_u32 s15, s19, 0
	s_add_i32 s47, s52, s29
	global_load_lds_dwordx4 v[210:211], off
	v_lshl_add_u64 v[220:221], s[14:15], 0, v[0:1]
	s_mov_b32 m0, s47
	v_lshl_add_u64 v[222:223], s[20:21], 0, v[130:131]
	global_load_lds_dwordx4 v[220:221], off
	v_lshl_add_u64 v[220:221], s[14:15], 0, v[130:131]
	s_add_i32 m0, s47, 0x2000
	s_nop 0
	global_load_lds_dwordx4 v[220:221], off
	v_lshl_add_u64 v[220:221], s[20:21], 0, v[0:1]
	s_mov_b32 m0, s30
	s_nop 0
	global_load_lds_dwordx4 v[220:221], off
	s_mov_b32 m0, s31
	s_nop 0
	global_load_lds_dwordx4 v[222:223], off
	s_waitcnt vmcnt(8)
	s_waitcnt lgkmcnt(0)
	s_barrier
	s_setprio 1
	v_mfma_f32_16x16x32_bf16 v[62:65], v[136:139], v[190:193], v[62:65]
	v_mfma_f32_16x16x32_bf16 v[58:61], v[166:169], v[190:193], v[58:61]
	v_mfma_f32_16x16x32_bf16 v[46:49], v[136:139], v[198:201], v[46:49]
	v_mfma_f32_16x16x32_bf16 v[42:45], v[166:169], v[198:201], v[42:45]
	v_mfma_f32_16x16x32_bf16 v[30:33], v[136:139], v[206:209], v[30:33]
	v_mfma_f32_16x16x32_bf16 v[26:29], v[166:169], v[206:209], v[26:29]
	v_mfma_f32_16x16x32_bf16 v[14:17], v[136:139], v[236:239], v[14:17]
	v_mfma_f32_16x16x32_bf16 v[10:13], v[166:169], v[236:239], v[10:13]
	v_mfma_f32_16x16x32_bf16 v[62:65], v[162:165], v[194:197], v[62:65]
	v_mfma_f32_16x16x32_bf16 v[58:61], v[170:173], v[194:197], v[58:61]
	v_mfma_f32_16x16x32_bf16 v[46:49], v[162:165], v[202:205], v[46:49]
	v_mfma_f32_16x16x32_bf16 v[42:45], v[170:173], v[202:205], v[42:45]
	v_mfma_f32_16x16x32_bf16 v[30:33], v[162:165], v[232:235], v[30:33]
	v_mfma_f32_16x16x32_bf16 v[26:29], v[170:173], v[232:235], v[26:29]
	v_mfma_f32_16x16x32_bf16 v[14:17], v[162:165], v[240:243], v[14:17]
	v_mfma_f32_16x16x32_bf16 v[10:13], v[170:173], v[240:243], v[10:13]
	v_mfma_f32_16x16x32_bf16 v[54:57], v[174:177], v[190:193], v[54:57]
	v_mfma_f32_16x16x32_bf16 v[50:53], v[182:185], v[190:193], v[50:53]
	v_mfma_f32_16x16x32_bf16 v[38:41], v[174:177], v[198:201], v[38:41]
	v_mfma_f32_16x16x32_bf16 v[34:37], v[182:185], v[198:201], v[34:37]
	v_mfma_f32_16x16x32_bf16 v[22:25], v[174:177], v[206:209], v[22:25]
	v_mfma_f32_16x16x32_bf16 v[18:21], v[182:185], v[206:209], v[18:21]
	v_mfma_f32_16x16x32_bf16 v[6:9], v[174:177], v[236:239], v[6:9]
	v_mfma_f32_16x16x32_bf16 v[2:5], v[182:185], v[236:239], v[2:5]
	v_mfma_f32_16x16x32_bf16 v[54:57], v[178:181], v[194:197], v[54:57]
	v_mfma_f32_16x16x32_bf16 v[50:53], v[186:189], v[194:197], v[50:53]
	v_mfma_f32_16x16x32_bf16 v[38:41], v[178:181], v[202:205], v[38:41]
	v_mfma_f32_16x16x32_bf16 v[34:37], v[186:189], v[202:205], v[34:37]
	v_mfma_f32_16x16x32_bf16 v[22:25], v[178:181], v[232:235], v[22:25]
	v_mfma_f32_16x16x32_bf16 v[18:21], v[186:189], v[232:235], v[18:21]
	v_mfma_f32_16x16x32_bf16 v[6:9], v[178:181], v[240:243], v[6:9]
	v_mfma_f32_16x16x32_bf16 v[2:5], v[186:189], v[240:243], v[2:5]
	s_setprio 0
	s_barrier
	s_add_i32 s47, 0, 0x18000
	v_add_u32_e32 v146, s47, v143
	s_add_i32 s52, 0, 0x1c000
	ds_read_b128 v[136:139], v146
	ds_read_b128 v[162:165], v146 offset:1024
	ds_read_b128 v[166:169], v146 offset:2048
	ds_read_b128 v[170:173], v146 offset:3072
	v_add_u32_e32 v146, s52, v143
	ds_read_b128 v[174:177], v146
	ds_read_b128 v[178:181], v146 offset:1024
	ds_read_b128 v[182:185], v146 offset:2048
	ds_read_b128 v[186:189], v146 offset:3072
	s_add_u32 s14, s20, 0xb0000
	s_addc_u32 s15, s21, 0
	s_mov_b32 m0, s34
	v_lshl_add_u64 v[244:245], s[14:15], 0, v[0:1]
	ds_read_b128 v[190:193], v145 offset:32768
	ds_read_b128 v[194:197], v145 offset:33792
	ds_read_b128 v[198:201], v145 offset:34816
	ds_read_b128 v[202:205], v145 offset:35840
	ds_read_b128 v[206:209], v145 offset:36864
	ds_read_b128 v[232:235], v145 offset:37888
	ds_read_b128 v[236:239], v145 offset:38912
	ds_read_b128 v[240:243], v145 offset:39936
	global_load_lds_dwordx4 v[244:245], off
	v_lshl_add_u64 v[244:245], s[14:15], 0, v[130:131]
	s_mov_b32 m0, s35
	s_nop 0
	global_load_lds_dwordx4 v[244:245], off
	s_waitcnt vmcnt(8)
	s_waitcnt lgkmcnt(0)
	s_barrier
	s_setprio 1
	v_mfma_f32_16x16x32_bf16 v[126:129], v[136:139], v[190:193], v[126:129]
	v_mfma_f32_16x16x32_bf16 v[122:125], v[166:169], v[190:193], v[122:125]
	v_mfma_f32_16x16x32_bf16 v[110:113], v[136:139], v[198:201], v[110:113]
	v_mfma_f32_16x16x32_bf16 v[106:109], v[166:169], v[198:201], v[106:109]
	v_mfma_f32_16x16x32_bf16 v[94:97], v[136:139], v[206:209], v[94:97]
	v_mfma_f32_16x16x32_bf16 v[90:93], v[166:169], v[206:209], v[90:93]
	v_mfma_f32_16x16x32_bf16 v[78:81], v[136:139], v[236:239], v[78:81]
	v_mfma_f32_16x16x32_bf16 v[74:77], v[166:169], v[236:239], v[74:77]
	v_mfma_f32_16x16x32_bf16 v[126:129], v[162:165], v[194:197], v[126:129]
	v_mfma_f32_16x16x32_bf16 v[122:125], v[170:173], v[194:197], v[122:125]
	v_mfma_f32_16x16x32_bf16 v[110:113], v[162:165], v[202:205], v[110:113]
	v_mfma_f32_16x16x32_bf16 v[106:109], v[170:173], v[202:205], v[106:109]
	v_mfma_f32_16x16x32_bf16 v[94:97], v[162:165], v[232:235], v[94:97]
	v_mfma_f32_16x16x32_bf16 v[90:93], v[170:173], v[232:235], v[90:93]
	v_mfma_f32_16x16x32_bf16 v[78:81], v[162:165], v[240:243], v[78:81]
	v_mfma_f32_16x16x32_bf16 v[74:77], v[170:173], v[240:243], v[74:77]
	v_mfma_f32_16x16x32_bf16 v[118:121], v[174:177], v[190:193], v[118:121]
	v_mfma_f32_16x16x32_bf16 v[114:117], v[182:185], v[190:193], v[114:117]
	v_mfma_f32_16x16x32_bf16 v[102:105], v[174:177], v[198:201], v[102:105]
	v_mfma_f32_16x16x32_bf16 v[98:101], v[182:185], v[198:201], v[98:101]
	v_mfma_f32_16x16x32_bf16 v[86:89], v[174:177], v[206:209], v[86:89]
	v_mfma_f32_16x16x32_bf16 v[82:85], v[182:185], v[206:209], v[82:85]
	v_mfma_f32_16x16x32_bf16 v[70:73], v[174:177], v[236:239], v[70:73]
	v_mfma_f32_16x16x32_bf16 v[66:69], v[182:185], v[236:239], v[66:69]
	v_mfma_f32_16x16x32_bf16 v[118:121], v[178:181], v[194:197], v[118:121]
	v_mfma_f32_16x16x32_bf16 v[114:117], v[186:189], v[194:197], v[114:117]
	v_mfma_f32_16x16x32_bf16 v[102:105], v[178:181], v[202:205], v[102:105]
	v_mfma_f32_16x16x32_bf16 v[98:101], v[186:189], v[202:205], v[98:101]
	v_mfma_f32_16x16x32_bf16 v[86:89], v[178:181], v[232:235], v[86:89]
	v_mfma_f32_16x16x32_bf16 v[82:85], v[186:189], v[232:235], v[82:85]
	v_mfma_f32_16x16x32_bf16 v[70:73], v[178:181], v[240:243], v[70:73]
	v_mfma_f32_16x16x32_bf16 v[66:69], v[186:189], v[240:243], v[66:69]
	s_setprio 0
	s_barrier
	s_add_i32 s14, s47, s29
	v_lshl_add_u64 v[140:141], v[140:141], 0, s[90:91]
	s_mov_b32 m0, s14
	ds_read_b128 v[190:193], v145 offset:49152
	ds_read_b128 v[194:197], v145 offset:50176
	ds_read_b128 v[198:201], v145 offset:51200
	ds_read_b128 v[202:205], v145 offset:52224
	ds_read_b128 v[206:209], v145 offset:53248
	ds_read_b128 v[232:235], v145 offset:54272
	ds_read_b128 v[236:239], v145 offset:55296
	ds_read_b128 v[240:243], v145 offset:56320
	global_load_lds_dwordx4 v[140:141], off
	s_add_i32 m0, s14, 0x2000
	s_add_u32 s14, s18, 0xb0080
	v_lshl_add_u64 v[140:141], v[210:211], 0, s[90:91]
	s_addc_u32 s15, s19, 0
	s_add_i32 s18, s52, s29
	global_load_lds_dwordx4 v[140:141], off
	v_lshl_add_u64 v[140:141], s[14:15], 0, v[0:1]
	s_mov_b32 m0, s18
	s_nop 0
	global_load_lds_dwordx4 v[140:141], off
	v_lshl_add_u64 v[140:141], s[14:15], 0, v[130:131]
	s_add_i32 m0, s18, 0x2000
	s_nop 0
	global_load_lds_dwordx4 v[140:141], off
	v_lshl_add_u64 v[140:141], v[220:221], 0, s[90:91]
	s_mov_b32 m0, s36
	s_nop 0
	global_load_lds_dwordx4 v[140:141], off
	v_lshl_add_u64 v[140:141], v[222:223], 0, s[90:91]
	s_mov_b32 m0, s37
	s_nop 0
	global_load_lds_dwordx4 v[140:141], off
	s_waitcnt vmcnt(8)
	s_waitcnt lgkmcnt(0)
	s_barrier
	s_setprio 1
	v_mfma_f32_16x16x32_bf16 v[62:65], v[136:139], v[190:193], v[62:65]
	v_mfma_f32_16x16x32_bf16 v[58:61], v[166:169], v[190:193], v[58:61]
	v_mfma_f32_16x16x32_bf16 v[46:49], v[136:139], v[198:201], v[46:49]
	v_mfma_f32_16x16x32_bf16 v[42:45], v[166:169], v[198:201], v[42:45]
	v_mfma_f32_16x16x32_bf16 v[30:33], v[136:139], v[206:209], v[30:33]
	v_mfma_f32_16x16x32_bf16 v[26:29], v[166:169], v[206:209], v[26:29]
	v_mfma_f32_16x16x32_bf16 v[14:17], v[136:139], v[236:239], v[14:17]
	v_mfma_f32_16x16x32_bf16 v[10:13], v[166:169], v[236:239], v[10:13]
	v_mfma_f32_16x16x32_bf16 v[62:65], v[162:165], v[194:197], v[62:65]
	v_mfma_f32_16x16x32_bf16 v[58:61], v[170:173], v[194:197], v[58:61]
	v_mfma_f32_16x16x32_bf16 v[46:49], v[162:165], v[202:205], v[46:49]
	v_mfma_f32_16x16x32_bf16 v[42:45], v[170:173], v[202:205], v[42:45]
	v_mfma_f32_16x16x32_bf16 v[30:33], v[162:165], v[232:235], v[30:33]
	v_mfma_f32_16x16x32_bf16 v[26:29], v[170:173], v[232:235], v[26:29]
	v_mfma_f32_16x16x32_bf16 v[14:17], v[162:165], v[240:243], v[14:17]
	v_mfma_f32_16x16x32_bf16 v[10:13], v[170:173], v[240:243], v[10:13]
	v_mfma_f32_16x16x32_bf16 v[54:57], v[174:177], v[190:193], v[54:57]
	v_mfma_f32_16x16x32_bf16 v[50:53], v[182:185], v[190:193], v[50:53]
	v_mfma_f32_16x16x32_bf16 v[38:41], v[174:177], v[198:201], v[38:41]
	v_mfma_f32_16x16x32_bf16 v[34:37], v[182:185], v[198:201], v[34:37]
	v_mfma_f32_16x16x32_bf16 v[22:25], v[174:177], v[206:209], v[22:25]
	v_mfma_f32_16x16x32_bf16 v[18:21], v[182:185], v[206:209], v[18:21]
	v_mfma_f32_16x16x32_bf16 v[6:9], v[174:177], v[236:239], v[6:9]
	v_mfma_f32_16x16x32_bf16 v[2:5], v[182:185], v[236:239], v[2:5]
	v_mfma_f32_16x16x32_bf16 v[54:57], v[178:181], v[194:197], v[54:57]
	v_mfma_f32_16x16x32_bf16 v[50:53], v[186:189], v[194:197], v[50:53]
	v_mfma_f32_16x16x32_bf16 v[38:41], v[178:181], v[202:205], v[38:41]
	v_mfma_f32_16x16x32_bf16 v[34:37], v[186:189], v[202:205], v[34:37]
	v_mfma_f32_16x16x32_bf16 v[22:25], v[178:181], v[232:235], v[22:25]
	v_mfma_f32_16x16x32_bf16 v[18:21], v[186:189], v[232:235], v[18:21]
	v_mfma_f32_16x16x32_bf16 v[6:9], v[178:181], v[240:243], v[6:9]
	v_mfma_f32_16x16x32_bf16 v[2:5], v[186:189], v[240:243], v[2:5]
	s_setprio 0
	s_barrier
	s_add_i32 s46, s46, 2
	s_add_u32 s44, s44, 0x100
	s_addc_u32 s45, s45, 0
	s_cmp_gt_u32 s46, 41
	s_mov_b64 s[14:15], s[16:17]
	s_cbranch_scc0 .LBB0_274
	s_and_b64 vcc, exec, s[10:11]
	s_cbranch_vccz .LBB0_277
	s_barrier

.LBB0_405:
	s_add_u32 s30, s28, 0xfffc0080
	s_addc_u32 s31, s29, -1
	s_add_i32 s56, 0, 0x10000
	s_cmp_eq_u32 s75, 12
	s_cselect_b32 s35, s21, s31
	s_cselect_b32 s34, s71, s30
	v_add_u32_e32 v140, s56, v143
	s_cselect_b32 s31, s19, s74
	s_cselect_b32 s30, s72, s73
	s_add_i32 s76, 0, 0x14000
	ds_read_b128 v[162:165], v140
	ds_read_b128 v[166:169], v140 offset:1024
	ds_read_b128 v[170:173], v140 offset:2048
	ds_read_b128 v[174:177], v140 offset:3072
	v_add_u32_e32 v140, s76, v143
	ds_read_b128 v[178:181], v140
	ds_read_b128 v[182:185], v140 offset:1024
	ds_read_b128 v[186:189], v140 offset:2048
	ds_read_b128 v[190:193], v140 offset:3072
	v_lshl_add_u64 v[140:141], s[28:29], 0, v[136:137]
	s_add_i32 m0, s25, 0xc000
	ds_read_b128 v[194:197], v145
	ds_read_b128 v[198:201], v145 offset:1024
	ds_read_b128 v[202:205], v145 offset:2048
	ds_read_b128 v[206:209], v145 offset:3072
	ds_read_b128 v[232:235], v145 offset:4096
	ds_read_b128 v[236:239], v145 offset:5120
	ds_read_b128 v[240:243], v145 offset:6144
	ds_read_b128 v[244:247], v145 offset:7168
	global_load_lds_dwordx4 v[140:141], off
	v_lshl_add_u64 v[140:141], s[28:29], 0, v[138:139]
	s_add_i32 m0, s25, 0xe000
	s_nop 0
	global_load_lds_dwordx4 v[140:141], off
	s_waitcnt vmcnt(8)
	s_waitcnt lgkmcnt(0)
	s_barrier
	s_setprio 1
	v_mfma_f32_16x16x32_bf16 v[126:129], v[162:165], v[194:197], v[126:129]
	v_mfma_f32_16x16x32_bf16 v[122:125], v[170:173], v[194:197], v[122:125]
	v_mfma_f32_16x16x32_bf16 v[118:121], v[162:165], v[202:205], v[118:121]
	v_mfma_f32_16x16x32_bf16 v[110:113], v[170:173], v[202:205], v[110:113]
	v_mfma_f32_16x16x32_bf16 v[102:105], v[162:165], v[232:235], v[102:105]
	v_mfma_f32_16x16x32_bf16 v[94:97], v[170:173], v[232:235], v[94:97]
	v_mfma_f32_16x16x32_bf16 v[86:89], v[162:165], v[240:243], v[86:89]
	v_mfma_f32_16x16x32_bf16 v[78:81], v[170:173], v[240:243], v[78:81]
	v_mfma_f32_16x16x32_bf16 v[126:129], v[166:169], v[198:201], v[126:129]
	v_mfma_f32_16x16x32_bf16 v[122:125], v[174:177], v[198:201], v[122:125]
	v_mfma_f32_16x16x32_bf16 v[118:121], v[166:169], v[206:209], v[118:121]
	v_mfma_f32_16x16x32_bf16 v[110:113], v[174:177], v[206:209], v[110:113]
	v_mfma_f32_16x16x32_bf16 v[102:105], v[166:169], v[236:239], v[102:105]
	v_mfma_f32_16x16x32_bf16 v[94:97], v[174:177], v[236:239], v[94:97]
	v_mfma_f32_16x16x32_bf16 v[86:89], v[166:169], v[244:247], v[86:89]
	v_mfma_f32_16x16x32_bf16 v[78:81], v[174:177], v[244:247], v[78:81]
	v_mfma_f32_16x16x32_bf16 v[114:117], v[178:181], v[194:197], v[114:117]
	v_mfma_f32_16x16x32_bf16 v[106:109], v[186:189], v[194:197], v[106:109]
	v_mfma_f32_16x16x32_bf16 v[98:101], v[178:181], v[202:205], v[98:101]
	v_mfma_f32_16x16x32_bf16 v[90:93], v[186:189], v[202:205], v[90:93]
	v_mfma_f32_16x16x32_bf16 v[82:85], v[178:181], v[232:235], v[82:85]
	v_mfma_f32_16x16x32_bf16 v[74:77], v[186:189], v[232:235], v[74:77]
	v_mfma_f32_16x16x32_bf16 v[70:73], v[178:181], v[240:243], v[70:73]
	v_mfma_f32_16x16x32_bf16 v[66:69], v[186:189], v[240:243], v[66:69]
	v_mfma_f32_16x16x32_bf16 v[114:117], v[182:185], v[198:201], v[114:117]
	v_mfma_f32_16x16x32_bf16 v[106:109], v[190:193], v[198:201], v[106:109]
	v_mfma_f32_16x16x32_bf16 v[98:101], v[182:185], v[206:209], v[98:101]
	v_mfma_f32_16x16x32_bf16 v[90:93], v[190:193], v[206:209], v[90:93]
	v_mfma_f32_16x16x32_bf16 v[82:85], v[182:185], v[236:239], v[82:85]
	v_mfma_f32_16x16x32_bf16 v[74:77], v[190:193], v[236:239], v[74:77]
	v_mfma_f32_16x16x32_bf16 v[70:73], v[182:185], v[244:247], v[70:73]
	v_mfma_f32_16x16x32_bf16 v[66:69], v[190:193], v[244:247], v[66:69]
	s_setprio 0
	s_barrier
	s_add_i32 s56, s56, s13
	v_lshl_add_u64 v[140:141], s[30:31], 0, v[0:1]
	s_mov_b32 m0, s56
	ds_read_b128 v[194:197], v145 offset:16384
	ds_read_b128 v[198:201], v145 offset:17408
	ds_read_b128 v[202:205], v145 offset:18432
	ds_read_b128 v[206:209], v145 offset:19456
	ds_read_b128 v[232:235], v145 offset:20480
	ds_read_b128 v[236:239], v145 offset:21504
	ds_read_b128 v[240:243], v145 offset:22528
	ds_read_b128 v[244:247], v145 offset:23552
	global_load_lds_dwordx4 v[140:141], off
	s_add_i32 m0, s56, 0x2000
	s_add_u32 s56, s30, 0x40000
	v_lshl_add_u64 v[210:211], s[30:31], 0, v[130:131]
	s_addc_u32 s57, s31, 0
	s_add_i32 s76, s76, s13
	global_load_lds_dwordx4 v[210:211], off
	v_lshl_add_u64 v[220:221], s[56:57], 0, v[0:1]
	s_mov_b32 m0, s76
	v_lshl_add_u64 v[222:223], s[34:35], 0, v[132:133]
	global_load_lds_dwordx4 v[220:221], off
	v_lshl_add_u64 v[220:221], s[56:57], 0, v[130:131]
	s_add_i32 m0, s76, 0x2000
	s_nop 0
	global_load_lds_dwordx4 v[220:221], off
	v_lshl_add_u64 v[220:221], s[34:35], 0, v[134:135]
	s_mov_b32 m0, s25
	s_nop 0
	global_load_lds_dwordx4 v[220:221], off
	s_mov_b32 m0, s47
	s_nop 0
	global_load_lds_dwordx4 v[222:223], off
	s_waitcnt vmcnt(8)
	s_waitcnt lgkmcnt(0)
	s_barrier
	s_setprio 1
	v_mfma_f32_16x16x32_bf16 v[62:65], v[162:165], v[194:197], v[62:65]
	v_mfma_f32_16x16x32_bf16 v[58:61], v[170:173], v[194:197], v[58:61]
	v_mfma_f32_16x16x32_bf16 v[54:57], v[162:165], v[202:205], v[54:57]
	v_mfma_f32_16x16x32_bf16 v[46:49], v[170:173], v[202:205], v[46:49]
	v_mfma_f32_16x16x32_bf16 v[38:41], v[162:165], v[232:235], v[38:41]
	v_mfma_f32_16x16x32_bf16 v[30:33], v[170:173], v[232:235], v[30:33]
	v_mfma_f32_16x16x32_bf16 v[22:25], v[162:165], v[240:243], v[22:25]
	v_mfma_f32_16x16x32_bf16 v[14:17], v[170:173], v[240:243], v[14:17]
	v_mfma_f32_16x16x32_bf16 v[62:65], v[166:169], v[198:201], v[62:65]
	v_mfma_f32_16x16x32_bf16 v[58:61], v[174:177], v[198:201], v[58:61]
	v_mfma_f32_16x16x32_bf16 v[54:57], v[166:169], v[206:209], v[54:57]
	v_mfma_f32_16x16x32_bf16 v[46:49], v[174:177], v[206:209], v[46:49]
	v_mfma_f32_16x16x32_bf16 v[38:41], v[166:169], v[236:239], v[38:41]
	v_mfma_f32_16x16x32_bf16 v[30:33], v[174:177], v[236:239], v[30:33]
	v_mfma_f32_16x16x32_bf16 v[22:25], v[166:169], v[244:247], v[22:25]
	v_mfma_f32_16x16x32_bf16 v[14:17], v[174:177], v[244:247], v[14:17]
	v_mfma_f32_16x16x32_bf16 v[50:53], v[178:181], v[194:197], v[50:53]
	v_mfma_f32_16x16x32_bf16 v[42:45], v[186:189], v[194:197], v[42:45]
	v_mfma_f32_16x16x32_bf16 v[34:37], v[178:181], v[202:205], v[34:37]
	v_mfma_f32_16x16x32_bf16 v[26:29], v[186:189], v[202:205], v[26:29]
	v_mfma_f32_16x16x32_bf16 v[18:21], v[178:181], v[232:235], v[18:21]
	v_mfma_f32_16x16x32_bf16 v[10:13], v[186:189], v[232:235], v[10:13]
	v_mfma_f32_16x16x32_bf16 v[6:9], v[178:181], v[240:243], v[6:9]
	v_mfma_f32_16x16x32_bf16 v[2:5], v[186:189], v[240:243], v[2:5]
	v_mfma_f32_16x16x32_bf16 v[50:53], v[182:185], v[198:201], v[50:53]
	v_mfma_f32_16x16x32_bf16 v[42:45], v[190:193], v[198:201], v[42:45]
	v_mfma_f32_16x16x32_bf16 v[34:37], v[182:185], v[206:209], v[34:37]
	v_mfma_f32_16x16x32_bf16 v[26:29], v[190:193], v[206:209], v[26:29]
	v_mfma_f32_16x16x32_bf16 v[18:21], v[182:185], v[236:239], v[18:21]
	v_mfma_f32_16x16x32_bf16 v[10:13], v[190:193], v[236:239], v[10:13]
	v_mfma_f32_16x16x32_bf16 v[6:9], v[182:185], v[244:247], v[6:9]
	v_mfma_f32_16x16x32_bf16 v[2:5], v[190:193], v[244:247], v[2:5]
	s_setprio 0
	s_barrier
	s_add_i32 s56, 0, 0x18000
	v_add_u32_e32 v146, s56, v143
	s_add_i32 s57, 0, 0x1c000
	ds_read_b128 v[162:165], v146
	ds_read_b128 v[166:169], v146 offset:1024
	ds_read_b128 v[170:173], v146 offset:2048
	ds_read_b128 v[174:177], v146 offset:3072
	v_add_u32_e32 v146, s57, v143
	ds_read_b128 v[178:181], v146
	ds_read_b128 v[182:185], v146 offset:1024
	ds_read_b128 v[186:189], v146 offset:2048
	ds_read_b128 v[190:193], v146 offset:3072
	s_add_u32 s34, s34, 0x40000
	s_addc_u32 s35, s35, 0
	s_mov_b32 m0, s52
	v_lshl_add_u64 v[248:249], s[34:35], 0, v[134:135]
	ds_read_b128 v[194:197], v145 offset:32768
	ds_read_b128 v[198:201], v145 offset:33792
	ds_read_b128 v[202:205], v145 offset:34816
	ds_read_b128 v[206:209], v145 offset:35840
	ds_read_b128 v[232:235], v145 offset:36864
	ds_read_b128 v[236:239], v145 offset:37888
	ds_read_b128 v[240:243], v145 offset:38912
	ds_read_b128 v[244:247], v145 offset:39936
	global_load_lds_dwordx4 v[248:249], off
	v_lshl_add_u64 v[248:249], s[34:35], 0, v[132:133]
	s_mov_b32 m0, s53
	s_nop 0
	global_load_lds_dwordx4 v[248:249], off
	s_waitcnt vmcnt(8)
	s_waitcnt lgkmcnt(0)
	s_barrier
	s_setprio 1
	v_mfma_f32_16x16x32_bf16 v[126:129], v[162:165], v[194:197], v[126:129]
	v_mfma_f32_16x16x32_bf16 v[122:125], v[170:173], v[194:197], v[122:125]
	v_mfma_f32_16x16x32_bf16 v[118:121], v[162:165], v[202:205], v[118:121]
	v_mfma_f32_16x16x32_bf16 v[110:113], v[170:173], v[202:205], v[110:113]
	v_mfma_f32_16x16x32_bf16 v[102:105], v[162:165], v[232:235], v[102:105]
	v_mfma_f32_16x16x32_bf16 v[94:97], v[170:173], v[232:235], v[94:97]
	v_mfma_f32_16x16x32_bf16 v[86:89], v[162:165], v[240:243], v[86:89]
	v_mfma_f32_16x16x32_bf16 v[78:81], v[170:173], v[240:243], v[78:81]
	v_mfma_f32_16x16x32_bf16 v[126:129], v[166:169], v[198:201], v[126:129]
	v_mfma_f32_16x16x32_bf16 v[122:125], v[174:177], v[198:201], v[122:125]
	v_mfma_f32_16x16x32_bf16 v[118:121], v[166:169], v[206:209], v[118:121]
	v_mfma_f32_16x16x32_bf16 v[110:113], v[174:177], v[206:209], v[110:113]
	v_mfma_f32_16x16x32_bf16 v[102:105], v[166:169], v[236:239], v[102:105]
	v_mfma_f32_16x16x32_bf16 v[94:97], v[174:177], v[236:239], v[94:97]
	v_mfma_f32_16x16x32_bf16 v[86:89], v[166:169], v[244:247], v[86:89]
	v_mfma_f32_16x16x32_bf16 v[78:81], v[174:177], v[244:247], v[78:81]
	v_mfma_f32_16x16x32_bf16 v[114:117], v[178:181], v[194:197], v[114:117]
	v_mfma_f32_16x16x32_bf16 v[106:109], v[186:189], v[194:197], v[106:109]
	v_mfma_f32_16x16x32_bf16 v[98:101], v[178:181], v[202:205], v[98:101]
	v_mfma_f32_16x16x32_bf16 v[90:93], v[186:189], v[202:205], v[90:93]
	v_mfma_f32_16x16x32_bf16 v[82:85], v[178:181], v[232:235], v[82:85]
	v_mfma_f32_16x16x32_bf16 v[74:77], v[186:189], v[232:235], v[74:77]
	v_mfma_f32_16x16x32_bf16 v[70:73], v[178:181], v[240:243], v[70:73]
	v_mfma_f32_16x16x32_bf16 v[66:69], v[186:189], v[240:243], v[66:69]
	v_mfma_f32_16x16x32_bf16 v[114:117], v[182:185], v[198:201], v[114:117]
	v_mfma_f32_16x16x32_bf16 v[106:109], v[190:193], v[198:201], v[106:109]
	v_mfma_f32_16x16x32_bf16 v[98:101], v[182:185], v[206:209], v[98:101]
	v_mfma_f32_16x16x32_bf16 v[90:93], v[190:193], v[206:209], v[90:93]
	v_mfma_f32_16x16x32_bf16 v[82:85], v[182:185], v[236:239], v[82:85]
	v_mfma_f32_16x16x32_bf16 v[74:77], v[190:193], v[236:239], v[74:77]
	v_mfma_f32_16x16x32_bf16 v[70:73], v[182:185], v[244:247], v[70:73]
	v_mfma_f32_16x16x32_bf16 v[66:69], v[190:193], v[244:247], v[66:69]
	s_setprio 0
	s_barrier
	s_add_i32 s34, s56, s13
	v_lshl_add_u64 v[140:141], v[140:141], 0, s[90:91]
	s_mov_b32 m0, s34
	ds_read_b128 v[194:197], v145 offset:49152
	ds_read_b128 v[198:201], v145 offset:50176
	ds_read_b128 v[202:205], v145 offset:51200
	ds_read_b128 v[206:209], v145 offset:52224
	ds_read_b128 v[232:235], v145 offset:53248
	ds_read_b128 v[236:239], v145 offset:54272
	ds_read_b128 v[240:243], v145 offset:55296
	ds_read_b128 v[244:247], v145 offset:56320
	global_load_lds_dwordx4 v[140:141], off
	s_add_i32 m0, s34, 0x2000
	s_add_u32 s30, s30, 0x40080
	v_lshl_add_u64 v[140:141], v[210:211], 0, s[90:91]
	s_addc_u32 s31, s31, 0
	s_add_i32 s34, s57, s13
	global_load_lds_dwordx4 v[140:141], off
	v_lshl_add_u64 v[140:141], s[30:31], 0, v[0:1]
	s_mov_b32 m0, s34
	s_nop 0
	global_load_lds_dwordx4 v[140:141], off
	v_lshl_add_u64 v[140:141], s[30:31], 0, v[130:131]
	s_add_i32 m0, s34, 0x2000
	s_nop 0
	global_load_lds_dwordx4 v[140:141], off
	v_lshl_add_u64 v[140:141], v[220:221], 0, s[90:91]
	s_mov_b32 m0, s54
	s_nop 0
	global_load_lds_dwordx4 v[140:141], off
	v_lshl_add_u64 v[140:141], v[222:223], 0, s[90:91]
	s_mov_b32 m0, s55
	s_nop 0
	global_load_lds_dwordx4 v[140:141], off
	s_waitcnt vmcnt(8)
	s_waitcnt lgkmcnt(0)
	s_barrier
	s_setprio 1
	v_mfma_f32_16x16x32_bf16 v[62:65], v[162:165], v[194:197], v[62:65]
	v_mfma_f32_16x16x32_bf16 v[58:61], v[170:173], v[194:197], v[58:61]
	v_mfma_f32_16x16x32_bf16 v[54:57], v[162:165], v[202:205], v[54:57]
	v_mfma_f32_16x16x32_bf16 v[46:49], v[170:173], v[202:205], v[46:49]
	v_mfma_f32_16x16x32_bf16 v[38:41], v[162:165], v[232:235], v[38:41]
	v_mfma_f32_16x16x32_bf16 v[30:33], v[170:173], v[232:235], v[30:33]
	v_mfma_f32_16x16x32_bf16 v[22:25], v[162:165], v[240:243], v[22:25]
	v_mfma_f32_16x16x32_bf16 v[14:17], v[170:173], v[240:243], v[14:17]
	v_mfma_f32_16x16x32_bf16 v[62:65], v[166:169], v[198:201], v[62:65]
	v_mfma_f32_16x16x32_bf16 v[58:61], v[174:177], v[198:201], v[58:61]
	v_mfma_f32_16x16x32_bf16 v[54:57], v[166:169], v[206:209], v[54:57]
	v_mfma_f32_16x16x32_bf16 v[46:49], v[174:177], v[206:209], v[46:49]
	v_mfma_f32_16x16x32_bf16 v[38:41], v[166:169], v[236:239], v[38:41]
	v_mfma_f32_16x16x32_bf16 v[30:33], v[174:177], v[236:239], v[30:33]
	v_mfma_f32_16x16x32_bf16 v[22:25], v[166:169], v[244:247], v[22:25]
	v_mfma_f32_16x16x32_bf16 v[14:17], v[174:177], v[244:247], v[14:17]
	v_mfma_f32_16x16x32_bf16 v[50:53], v[178:181], v[194:197], v[50:53]
	v_mfma_f32_16x16x32_bf16 v[42:45], v[186:189], v[194:197], v[42:45]
	v_mfma_f32_16x16x32_bf16 v[34:37], v[178:181], v[202:205], v[34:37]
	v_mfma_f32_16x16x32_bf16 v[26:29], v[186:189], v[202:205], v[26:29]
	v_mfma_f32_16x16x32_bf16 v[18:21], v[178:181], v[232:235], v[18:21]
	v_mfma_f32_16x16x32_bf16 v[10:13], v[186:189], v[232:235], v[10:13]
	v_mfma_f32_16x16x32_bf16 v[6:9], v[178:181], v[240:243], v[6:9]
	v_mfma_f32_16x16x32_bf16 v[2:5], v[186:189], v[240:243], v[2:5]
	v_mfma_f32_16x16x32_bf16 v[50:53], v[182:185], v[198:201], v[50:53]
	v_mfma_f32_16x16x32_bf16 v[42:45], v[190:193], v[198:201], v[42:45]
	v_mfma_f32_16x16x32_bf16 v[34:37], v[182:185], v[206:209], v[34:37]
	v_mfma_f32_16x16x32_bf16 v[26:29], v[190:193], v[206:209], v[26:29]
	v_mfma_f32_16x16x32_bf16 v[18:21], v[182:185], v[236:239], v[18:21]
	v_mfma_f32_16x16x32_bf16 v[10:13], v[190:193], v[236:239], v[10:13]
	v_mfma_f32_16x16x32_bf16 v[6:9], v[182:185], v[244:247], v[6:9]
	v_mfma_f32_16x16x32_bf16 v[2:5], v[190:193], v[244:247], v[2:5]
	s_setprio 0
	s_barrier
	s_add_i32 s75, s75, 2
	s_add_u32 s28, s28, 0x100
	s_addc_u32 s29, s29, 0
	s_add_u32 s73, s73, 0x100
	s_addc_u32 s74, s74, 0
	s_cmp_gt_u32 s75, 13
	s_cbranch_scc0 .LBB0_405
	s_and_b64 vcc, exec, s[16:17]
	s_cbranch_vccz .LBB0_408
	s_barrier

.LBB0_546:
	s_add_u32 s18, s16, 0x100
	s_addc_u32 s19, s17, 0
	s_add_i32 s53, 0, 0x10000
	s_cmp_eq_u32 s52, 2
	s_cselect_b32 s23, s7, s19
	s_cselect_b32 s22, s6, s18
	v_add_u32_e32 v144, s53, v141
	s_cselect_b32 s21, s15, s47
	s_cselect_b32 s20, s14, s46
	s_add_i32 s54, 0, 0x14000
	ds_read_b128 v[162:165], v144
	ds_read_b128 v[166:169], v144 offset:1024
	ds_read_b128 v[170:173], v144 offset:2048
	ds_read_b128 v[174:177], v144 offset:3072
	v_add_u32_e32 v144, s54, v141
	ds_read_b128 v[178:181], v144
	ds_read_b128 v[182:185], v144 offset:1024
	ds_read_b128 v[186:189], v144 offset:2048
	ds_read_b128 v[190:193], v144 offset:3072
	v_lshl_add_u64 v[144:145], s[16:17], 0, v[136:137]
	s_add_i32 m0, s34, 0xc000
	ds_read_b128 v[194:197], v143
	ds_read_b128 v[198:201], v143 offset:1024
	ds_read_b128 v[202:205], v143 offset:2048
	ds_read_b128 v[206:209], v143 offset:3072
	ds_read_b128 v[232:235], v143 offset:4096
	ds_read_b128 v[236:239], v143 offset:5120
	ds_read_b128 v[240:243], v143 offset:6144
	ds_read_b128 v[244:247], v143 offset:7168
	global_load_lds_dwordx4 v[144:145], off
	v_lshl_add_u64 v[144:145], s[16:17], 0, v[138:139]
	s_add_i32 m0, s34, 0xe000
	s_nop 0
	global_load_lds_dwordx4 v[144:145], off
	s_waitcnt vmcnt(8)
	s_waitcnt lgkmcnt(0)
	s_barrier
	s_setprio 1
	v_mfma_f32_16x16x32_bf16 v[126:129], v[162:165], v[194:197], v[126:129]
	v_mfma_f32_16x16x32_bf16 v[122:125], v[170:173], v[194:197], v[122:125]
	v_mfma_f32_16x16x32_bf16 v[118:121], v[162:165], v[202:205], v[118:121]
	v_mfma_f32_16x16x32_bf16 v[110:113], v[170:173], v[202:205], v[110:113]
	v_mfma_f32_16x16x32_bf16 v[102:105], v[162:165], v[232:235], v[102:105]
	v_mfma_f32_16x16x32_bf16 v[94:97], v[170:173], v[232:235], v[94:97]
	v_mfma_f32_16x16x32_bf16 v[86:89], v[162:165], v[240:243], v[86:89]
	v_mfma_f32_16x16x32_bf16 v[78:81], v[170:173], v[240:243], v[78:81]
	v_mfma_f32_16x16x32_bf16 v[126:129], v[166:169], v[198:201], v[126:129]
	v_mfma_f32_16x16x32_bf16 v[122:125], v[174:177], v[198:201], v[122:125]
	v_mfma_f32_16x16x32_bf16 v[118:121], v[166:169], v[206:209], v[118:121]
	v_mfma_f32_16x16x32_bf16 v[110:113], v[174:177], v[206:209], v[110:113]
	v_mfma_f32_16x16x32_bf16 v[102:105], v[166:169], v[236:239], v[102:105]
	v_mfma_f32_16x16x32_bf16 v[94:97], v[174:177], v[236:239], v[94:97]
	v_mfma_f32_16x16x32_bf16 v[86:89], v[166:169], v[244:247], v[86:89]
	v_mfma_f32_16x16x32_bf16 v[78:81], v[174:177], v[244:247], v[78:81]
	v_mfma_f32_16x16x32_bf16 v[114:117], v[178:181], v[194:197], v[114:117]
	v_mfma_f32_16x16x32_bf16 v[106:109], v[186:189], v[194:197], v[106:109]
	v_mfma_f32_16x16x32_bf16 v[98:101], v[178:181], v[202:205], v[98:101]
	v_mfma_f32_16x16x32_bf16 v[90:93], v[186:189], v[202:205], v[90:93]
	v_mfma_f32_16x16x32_bf16 v[82:85], v[178:181], v[232:235], v[82:85]
	v_mfma_f32_16x16x32_bf16 v[74:77], v[186:189], v[232:235], v[74:77]
	v_mfma_f32_16x16x32_bf16 v[70:73], v[178:181], v[240:243], v[70:73]
	v_mfma_f32_16x16x32_bf16 v[66:69], v[186:189], v[240:243], v[66:69]
	v_mfma_f32_16x16x32_bf16 v[114:117], v[182:185], v[198:201], v[114:117]
	v_mfma_f32_16x16x32_bf16 v[106:109], v[190:193], v[198:201], v[106:109]
	v_mfma_f32_16x16x32_bf16 v[98:101], v[182:185], v[206:209], v[98:101]
	v_mfma_f32_16x16x32_bf16 v[90:93], v[190:193], v[206:209], v[90:93]
	v_mfma_f32_16x16x32_bf16 v[82:85], v[182:185], v[236:239], v[82:85]
	v_mfma_f32_16x16x32_bf16 v[74:77], v[190:193], v[236:239], v[74:77]
	v_mfma_f32_16x16x32_bf16 v[70:73], v[182:185], v[244:247], v[70:73]
	v_mfma_f32_16x16x32_bf16 v[66:69], v[190:193], v[244:247], v[66:69]
	s_setprio 0
	s_barrier
	s_add_i32 s16, s53, s30
	v_lshl_add_u64 v[144:145], s[20:21], 0, v[0:1]
	s_mov_b32 m0, s16
	ds_read_b128 v[194:197], v143 offset:16384
	ds_read_b128 v[198:201], v143 offset:17408
	ds_read_b128 v[202:205], v143 offset:18432
	ds_read_b128 v[206:209], v143 offset:19456
	ds_read_b128 v[232:235], v143 offset:20480
	ds_read_b128 v[236:239], v143 offset:21504
	ds_read_b128 v[240:243], v143 offset:22528
	ds_read_b128 v[244:247], v143 offset:23552
	global_load_lds_dwordx4 v[144:145], off
	s_add_i32 m0, s16, 0x2000
	s_add_u32 s16, s20, 0x18000
	v_lshl_add_u64 v[210:211], s[20:21], 0, v[130:131]
	s_addc_u32 s17, s21, 0
	s_add_i32 s53, s54, s30
	global_load_lds_dwordx4 v[210:211], off
	v_lshl_add_u64 v[220:221], s[16:17], 0, v[0:1]
	s_mov_b32 m0, s53
	v_lshl_add_u64 v[222:223], s[22:23], 0, v[132:133]
	global_load_lds_dwordx4 v[220:221], off
	v_lshl_add_u64 v[220:221], s[16:17], 0, v[130:131]
	s_add_i32 m0, s53, 0x2000
	s_nop 0
	global_load_lds_dwordx4 v[220:221], off
	v_lshl_add_u64 v[220:221], s[22:23], 0, v[134:135]
	s_mov_b32 m0, s34
	s_nop 0
	global_load_lds_dwordx4 v[220:221], off
	s_mov_b32 m0, s35
	s_nop 0
	global_load_lds_dwordx4 v[222:223], off
	s_waitcnt vmcnt(8)
	s_waitcnt lgkmcnt(0)
	s_barrier
	s_setprio 1
	v_mfma_f32_16x16x32_bf16 v[62:65], v[162:165], v[194:197], v[62:65]
	v_mfma_f32_16x16x32_bf16 v[58:61], v[170:173], v[194:197], v[58:61]
	v_mfma_f32_16x16x32_bf16 v[54:57], v[162:165], v[202:205], v[54:57]
	v_mfma_f32_16x16x32_bf16 v[46:49], v[170:173], v[202:205], v[46:49]
	v_mfma_f32_16x16x32_bf16 v[38:41], v[162:165], v[232:235], v[38:41]
	v_mfma_f32_16x16x32_bf16 v[30:33], v[170:173], v[232:235], v[30:33]
	v_mfma_f32_16x16x32_bf16 v[22:25], v[162:165], v[240:243], v[22:25]
	v_mfma_f32_16x16x32_bf16 v[14:17], v[170:173], v[240:243], v[14:17]
	v_mfma_f32_16x16x32_bf16 v[62:65], v[166:169], v[198:201], v[62:65]
	v_mfma_f32_16x16x32_bf16 v[58:61], v[174:177], v[198:201], v[58:61]
	v_mfma_f32_16x16x32_bf16 v[54:57], v[166:169], v[206:209], v[54:57]
	v_mfma_f32_16x16x32_bf16 v[46:49], v[174:177], v[206:209], v[46:49]
	v_mfma_f32_16x16x32_bf16 v[38:41], v[166:169], v[236:239], v[38:41]
	v_mfma_f32_16x16x32_bf16 v[30:33], v[174:177], v[236:239], v[30:33]
	v_mfma_f32_16x16x32_bf16 v[22:25], v[166:169], v[244:247], v[22:25]
	v_mfma_f32_16x16x32_bf16 v[14:17], v[174:177], v[244:247], v[14:17]
	v_mfma_f32_16x16x32_bf16 v[50:53], v[178:181], v[194:197], v[50:53]
	v_mfma_f32_16x16x32_bf16 v[42:45], v[186:189], v[194:197], v[42:45]
	v_mfma_f32_16x16x32_bf16 v[34:37], v[178:181], v[202:205], v[34:37]
	v_mfma_f32_16x16x32_bf16 v[26:29], v[186:189], v[202:205], v[26:29]
	v_mfma_f32_16x16x32_bf16 v[18:21], v[178:181], v[232:235], v[18:21]
	v_mfma_f32_16x16x32_bf16 v[10:13], v[186:189], v[232:235], v[10:13]
	v_mfma_f32_16x16x32_bf16 v[6:9], v[178:181], v[240:243], v[6:9]
	v_mfma_f32_16x16x32_bf16 v[2:5], v[186:189], v[240:243], v[2:5]
	v_mfma_f32_16x16x32_bf16 v[50:53], v[182:185], v[198:201], v[50:53]
	v_mfma_f32_16x16x32_bf16 v[42:45], v[190:193], v[198:201], v[42:45]
	v_mfma_f32_16x16x32_bf16 v[34:37], v[182:185], v[206:209], v[34:37]
	v_mfma_f32_16x16x32_bf16 v[26:29], v[190:193], v[206:209], v[26:29]
	v_mfma_f32_16x16x32_bf16 v[18:21], v[182:185], v[236:239], v[18:21]
	v_mfma_f32_16x16x32_bf16 v[10:13], v[190:193], v[236:239], v[10:13]
	v_mfma_f32_16x16x32_bf16 v[6:9], v[182:185], v[244:247], v[6:9]
	v_mfma_f32_16x16x32_bf16 v[2:5], v[190:193], v[244:247], v[2:5]
	s_setprio 0
	s_barrier
	s_add_i32 s53, 0, 0x18000
	v_add_u32_e32 v146, s53, v141
	s_add_i32 s54, 0, 0x1c000
	ds_read_b128 v[162:165], v146
	ds_read_b128 v[166:169], v146 offset:1024
	ds_read_b128 v[170:173], v146 offset:2048
	ds_read_b128 v[174:177], v146 offset:3072
	v_add_u32_e32 v146, s54, v141
	ds_read_b128 v[178:181], v146
	ds_read_b128 v[182:185], v146 offset:1024
	ds_read_b128 v[186:189], v146 offset:2048
	ds_read_b128 v[190:193], v146 offset:3072
	s_add_u32 s16, s22, 0x18000
	s_addc_u32 s17, s23, 0
	s_mov_b32 m0, s36
	v_lshl_add_u64 v[248:249], s[16:17], 0, v[134:135]
	ds_read_b128 v[194:197], v143 offset:32768
	ds_read_b128 v[198:201], v143 offset:33792
	ds_read_b128 v[202:205], v143 offset:34816
	ds_read_b128 v[206:209], v143 offset:35840
	ds_read_b128 v[232:235], v143 offset:36864
	ds_read_b128 v[236:239], v143 offset:37888
	ds_read_b128 v[240:243], v143 offset:38912
	ds_read_b128 v[244:247], v143 offset:39936
	global_load_lds_dwordx4 v[248:249], off
	v_lshl_add_u64 v[248:249], s[16:17], 0, v[132:133]
	s_mov_b32 m0, s37
	s_nop 0
	global_load_lds_dwordx4 v[248:249], off
	s_waitcnt vmcnt(8)
	s_waitcnt lgkmcnt(0)
	s_barrier
	s_setprio 1
	v_mfma_f32_16x16x32_bf16 v[126:129], v[162:165], v[194:197], v[126:129]
	v_mfma_f32_16x16x32_bf16 v[122:125], v[170:173], v[194:197], v[122:125]
	v_mfma_f32_16x16x32_bf16 v[118:121], v[162:165], v[202:205], v[118:121]
	v_mfma_f32_16x16x32_bf16 v[110:113], v[170:173], v[202:205], v[110:113]
	v_mfma_f32_16x16x32_bf16 v[102:105], v[162:165], v[232:235], v[102:105]
	v_mfma_f32_16x16x32_bf16 v[94:97], v[170:173], v[232:235], v[94:97]
	v_mfma_f32_16x16x32_bf16 v[86:89], v[162:165], v[240:243], v[86:89]
	v_mfma_f32_16x16x32_bf16 v[78:81], v[170:173], v[240:243], v[78:81]
	v_mfma_f32_16x16x32_bf16 v[126:129], v[166:169], v[198:201], v[126:129]
	v_mfma_f32_16x16x32_bf16 v[122:125], v[174:177], v[198:201], v[122:125]
	v_mfma_f32_16x16x32_bf16 v[118:121], v[166:169], v[206:209], v[118:121]
	v_mfma_f32_16x16x32_bf16 v[110:113], v[174:177], v[206:209], v[110:113]
	v_mfma_f32_16x16x32_bf16 v[102:105], v[166:169], v[236:239], v[102:105]
	v_mfma_f32_16x16x32_bf16 v[94:97], v[174:177], v[236:239], v[94:97]
	v_mfma_f32_16x16x32_bf16 v[86:89], v[166:169], v[244:247], v[86:89]
	v_mfma_f32_16x16x32_bf16 v[78:81], v[174:177], v[244:247], v[78:81]
	v_mfma_f32_16x16x32_bf16 v[114:117], v[178:181], v[194:197], v[114:117]
	v_mfma_f32_16x16x32_bf16 v[106:109], v[186:189], v[194:197], v[106:109]
	v_mfma_f32_16x16x32_bf16 v[98:101], v[178:181], v[202:205], v[98:101]
	v_mfma_f32_16x16x32_bf16 v[90:93], v[186:189], v[202:205], v[90:93]
	v_mfma_f32_16x16x32_bf16 v[82:85], v[178:181], v[232:235], v[82:85]
	v_mfma_f32_16x16x32_bf16 v[74:77], v[186:189], v[232:235], v[74:77]
	v_mfma_f32_16x16x32_bf16 v[70:73], v[178:181], v[240:243], v[70:73]
	v_mfma_f32_16x16x32_bf16 v[66:69], v[186:189], v[240:243], v[66:69]
	v_mfma_f32_16x16x32_bf16 v[114:117], v[182:185], v[198:201], v[114:117]
	v_mfma_f32_16x16x32_bf16 v[106:109], v[190:193], v[198:201], v[106:109]
	v_mfma_f32_16x16x32_bf16 v[98:101], v[182:185], v[206:209], v[98:101]
	v_mfma_f32_16x16x32_bf16 v[90:93], v[190:193], v[206:209], v[90:93]
	v_mfma_f32_16x16x32_bf16 v[82:85], v[182:185], v[236:239], v[82:85]
	v_mfma_f32_16x16x32_bf16 v[74:77], v[190:193], v[236:239], v[74:77]
	v_mfma_f32_16x16x32_bf16 v[70:73], v[182:185], v[244:247], v[70:73]
	v_mfma_f32_16x16x32_bf16 v[66:69], v[190:193], v[244:247], v[66:69]
	s_setprio 0
	s_barrier
	s_add_i32 s16, s53, s30
	v_lshl_add_u64 v[144:145], v[144:145], 0, s[90:91]
	s_mov_b32 m0, s16
	ds_read_b128 v[194:197], v143 offset:49152
	ds_read_b128 v[198:201], v143 offset:50176
	ds_read_b128 v[202:205], v143 offset:51200
	ds_read_b128 v[206:209], v143 offset:52224
	ds_read_b128 v[232:235], v143 offset:53248
	ds_read_b128 v[236:239], v143 offset:54272
	ds_read_b128 v[240:243], v143 offset:55296
	ds_read_b128 v[244:247], v143 offset:56320
	global_load_lds_dwordx4 v[144:145], off
	s_add_i32 m0, s16, 0x2000
	s_add_u32 s16, s20, 0x18080
	v_lshl_add_u64 v[144:145], v[210:211], 0, s[90:91]
	s_addc_u32 s17, s21, 0
	s_add_i32 s20, s54, s30
	global_load_lds_dwordx4 v[144:145], off
	v_lshl_add_u64 v[144:145], s[16:17], 0, v[0:1]
	s_mov_b32 m0, s20
	s_nop 0
	global_load_lds_dwordx4 v[144:145], off
	v_lshl_add_u64 v[144:145], s[16:17], 0, v[130:131]
	s_add_i32 m0, s20, 0x2000
	s_nop 0
	global_load_lds_dwordx4 v[144:145], off
	v_lshl_add_u64 v[144:145], v[220:221], 0, s[90:91]
	s_mov_b32 m0, s38
	s_nop 0
	global_load_lds_dwordx4 v[144:145], off
	v_lshl_add_u64 v[144:145], v[222:223], 0, s[90:91]
	s_mov_b32 m0, s39
	s_nop 0
	global_load_lds_dwordx4 v[144:145], off
	s_waitcnt vmcnt(8)
	s_waitcnt lgkmcnt(0)
	s_barrier
	s_setprio 1
	v_mfma_f32_16x16x32_bf16 v[62:65], v[162:165], v[194:197], v[62:65]
	v_mfma_f32_16x16x32_bf16 v[58:61], v[170:173], v[194:197], v[58:61]
	v_mfma_f32_16x16x32_bf16 v[54:57], v[162:165], v[202:205], v[54:57]
	v_mfma_f32_16x16x32_bf16 v[46:49], v[170:173], v[202:205], v[46:49]
	v_mfma_f32_16x16x32_bf16 v[38:41], v[162:165], v[232:235], v[38:41]
	v_mfma_f32_16x16x32_bf16 v[30:33], v[170:173], v[232:235], v[30:33]
	v_mfma_f32_16x16x32_bf16 v[22:25], v[162:165], v[240:243], v[22:25]
	v_mfma_f32_16x16x32_bf16 v[14:17], v[170:173], v[240:243], v[14:17]
	v_mfma_f32_16x16x32_bf16 v[62:65], v[166:169], v[198:201], v[62:65]
	v_mfma_f32_16x16x32_bf16 v[58:61], v[174:177], v[198:201], v[58:61]
	v_mfma_f32_16x16x32_bf16 v[54:57], v[166:169], v[206:209], v[54:57]
	v_mfma_f32_16x16x32_bf16 v[46:49], v[174:177], v[206:209], v[46:49]
	v_mfma_f32_16x16x32_bf16 v[38:41], v[166:169], v[236:239], v[38:41]
	v_mfma_f32_16x16x32_bf16 v[30:33], v[174:177], v[236:239], v[30:33]
	v_mfma_f32_16x16x32_bf16 v[22:25], v[166:169], v[244:247], v[22:25]
	v_mfma_f32_16x16x32_bf16 v[14:17], v[174:177], v[244:247], v[14:17]
	v_mfma_f32_16x16x32_bf16 v[50:53], v[178:181], v[194:197], v[50:53]
	v_mfma_f32_16x16x32_bf16 v[42:45], v[186:189], v[194:197], v[42:45]
	v_mfma_f32_16x16x32_bf16 v[34:37], v[178:181], v[202:205], v[34:37]
	v_mfma_f32_16x16x32_bf16 v[26:29], v[186:189], v[202:205], v[26:29]
	v_mfma_f32_16x16x32_bf16 v[18:21], v[178:181], v[232:235], v[18:21]
	v_mfma_f32_16x16x32_bf16 v[10:13], v[186:189], v[232:235], v[10:13]
	v_mfma_f32_16x16x32_bf16 v[6:9], v[178:181], v[240:243], v[6:9]
	v_mfma_f32_16x16x32_bf16 v[2:5], v[186:189], v[240:243], v[2:5]
	v_mfma_f32_16x16x32_bf16 v[50:53], v[182:185], v[198:201], v[50:53]
	v_mfma_f32_16x16x32_bf16 v[42:45], v[190:193], v[198:201], v[42:45]
	v_mfma_f32_16x16x32_bf16 v[34:37], v[182:185], v[206:209], v[34:37]
	v_mfma_f32_16x16x32_bf16 v[26:29], v[190:193], v[206:209], v[26:29]
	v_mfma_f32_16x16x32_bf16 v[18:21], v[182:185], v[236:239], v[18:21]
	v_mfma_f32_16x16x32_bf16 v[10:13], v[190:193], v[236:239], v[10:13]
	v_mfma_f32_16x16x32_bf16 v[6:9], v[182:185], v[244:247], v[6:9]
	v_mfma_f32_16x16x32_bf16 v[2:5], v[190:193], v[244:247], v[2:5]
	s_setprio 0
	s_barrier
	s_add_i32 s52, s52, 2
	s_add_u32 s46, s46, 0x100
	s_addc_u32 s47, s47, 0
	s_cmp_gt_u32 s52, 3
	s_mov_b64 s[16:17], s[18:19]
	s_cbranch_scc0 .LBB0_546
	s_and_b64 vcc, exec, s[12:13]
	s_cbranch_vccz .LBB0_549
	s_barrier

.LBB0_570:
	s_add_u32 s31, s24, s30
	s_addc_u32 s38, s25, 0
	s_add_u32 s36, s31, 0x100
	s_addc_u32 s37, s38, 0
	s_and_b64 s[34:35], s[28:29], exec
	s_cselect_b32 s35, s15, s37
	s_cselect_b32 s34, s76, s36
	s_add_u32 s30, s22, s30
	s_addc_u32 s36, s23, 0
	s_add_u32 s30, s30, 0x100
	s_addc_u32 s36, s36, 0
	s_add_i32 s56, 0, 0x10000
	s_and_b64 s[28:29], s[28:29], exec
	s_cselect_b32 s37, s13, s36
	s_cselect_b32 s36, s77, s30
	s_add_i32 s29, 0, 0x14000
	s_add_u32 s40, s31, 0x10080
	s_addc_u32 s41, s38, 0
	s_add_i32 vcc_lo, s56, s53
	s_add_i32 m0, s19, 0xc000
	s_add_i32 s57, s19, 0xe000
	s_add_i32 s82, vcc_lo, 0x2000
	v_add_u32_e32 v136, s56, v139
	s_add_u32 s38, s36, 0x10000
	ds_read_b128 v[142:145], v136
	ds_read_b128 v[162:165], v136 offset:1024
	ds_read_b128 v[166:169], v136 offset:2048
	ds_read_b128 v[170:173], v136 offset:3072
	v_add_u32_e32 v136, s29, v139
	s_addc_u32 s39, s37, 0
	s_add_i32 s96, s29, s53
	ds_read_b128 v[174:177], v136
	ds_read_b128 v[178:181], v136 offset:1024
	ds_read_b128 v[182:185], v136 offset:2048
	ds_read_b128 v[186:189], v136 offset:3072
	s_add_i32 s83, s96, 0x2000
	s_add_i32 s81, 0, 0x18000
	s_add_i32 s80, 0, 0x1c000
	s_add_u32 s30, s34, 0x10000
	s_addc_u32 s31, s35, 0
	s_add_i32 s79, s81, s53
	s_add_i32 s78, s79, 0x2000
	s_add_u32 s28, s36, 0x10080
	s_addc_u32 s29, s37, 0
	s_add_i32 vcc_hi, s80, s53
	s_add_i32 s56, vcc_hi, 0x2000
	v_lshl_add_u64 v[136:137], s[40:41], 0, v[130:131]
	ds_read_b128 v[190:193], v141
	ds_read_b128 v[194:197], v141 offset:1024
	ds_read_b128 v[198:201], v141 offset:2048
	ds_read_b128 v[202:205], v141 offset:3072
	ds_read_b128 v[206:209], v141 offset:4096
	ds_read_b128 v[232:235], v141 offset:5120
	ds_read_b128 v[236:239], v141 offset:6144
	ds_read_b128 v[240:243], v141 offset:7168
	global_load_lds_dwordx4 v[136:137], off
	v_lshl_add_u64 v[136:137], s[40:41], 0, v[132:133]
	s_mov_b32 m0, s57
	s_nop 0
	global_load_lds_dwordx4 v[136:137], off
	s_waitcnt vmcnt(8)
	s_waitcnt lgkmcnt(0)
	s_barrier
	s_setprio 1
	v_mfma_f32_16x16x32_bf16 v[126:129], v[142:145], v[190:193], v[126:129]
	v_mfma_f32_16x16x32_bf16 v[122:125], v[166:169], v[190:193], v[122:125]
	v_mfma_f32_16x16x32_bf16 v[118:121], v[142:145], v[198:201], v[118:121]
	v_mfma_f32_16x16x32_bf16 v[110:113], v[166:169], v[198:201], v[110:113]
	v_mfma_f32_16x16x32_bf16 v[102:105], v[142:145], v[206:209], v[102:105]
	v_mfma_f32_16x16x32_bf16 v[94:97], v[166:169], v[206:209], v[94:97]
	v_mfma_f32_16x16x32_bf16 v[86:89], v[142:145], v[236:239], v[86:89]
	v_mfma_f32_16x16x32_bf16 v[78:81], v[166:169], v[236:239], v[78:81]
	v_mfma_f32_16x16x32_bf16 v[126:129], v[162:165], v[194:197], v[126:129]
	v_mfma_f32_16x16x32_bf16 v[122:125], v[170:173], v[194:197], v[122:125]
	v_mfma_f32_16x16x32_bf16 v[118:121], v[162:165], v[202:205], v[118:121]
	v_mfma_f32_16x16x32_bf16 v[110:113], v[170:173], v[202:205], v[110:113]
	v_mfma_f32_16x16x32_bf16 v[102:105], v[162:165], v[232:235], v[102:105]
	v_mfma_f32_16x16x32_bf16 v[94:97], v[170:173], v[232:235], v[94:97]
	v_mfma_f32_16x16x32_bf16 v[86:89], v[162:165], v[240:243], v[86:89]
	v_mfma_f32_16x16x32_bf16 v[78:81], v[170:173], v[240:243], v[78:81]
	v_mfma_f32_16x16x32_bf16 v[114:117], v[174:177], v[190:193], v[114:117]
	v_mfma_f32_16x16x32_bf16 v[106:109], v[182:185], v[190:193], v[106:109]
	v_mfma_f32_16x16x32_bf16 v[98:101], v[174:177], v[198:201], v[98:101]
	v_mfma_f32_16x16x32_bf16 v[90:93], v[182:185], v[198:201], v[90:93]
	v_mfma_f32_16x16x32_bf16 v[82:85], v[174:177], v[206:209], v[82:85]
	v_mfma_f32_16x16x32_bf16 v[74:77], v[182:185], v[206:209], v[74:77]
	v_mfma_f32_16x16x32_bf16 v[70:73], v[174:177], v[236:239], v[70:73]
	v_mfma_f32_16x16x32_bf16 v[66:69], v[182:185], v[236:239], v[66:69]
	v_mfma_f32_16x16x32_bf16 v[114:117], v[178:181], v[194:197], v[114:117]
	v_mfma_f32_16x16x32_bf16 v[106:109], v[186:189], v[194:197], v[106:109]
	v_mfma_f32_16x16x32_bf16 v[98:101], v[178:181], v[202:205], v[98:101]
	v_mfma_f32_16x16x32_bf16 v[90:93], v[186:189], v[202:205], v[90:93]
	v_mfma_f32_16x16x32_bf16 v[82:85], v[178:181], v[232:235], v[82:85]
	v_mfma_f32_16x16x32_bf16 v[74:77], v[186:189], v[232:235], v[74:77]
	v_mfma_f32_16x16x32_bf16 v[70:73], v[178:181], v[240:243], v[70:73]
	v_mfma_f32_16x16x32_bf16 v[66:69], v[186:189], v[240:243], v[66:69]
	s_setprio 0
	s_barrier
	s_mov_b32 m0, vcc_lo
	v_lshl_add_u64 v[136:137], s[36:37], 0, v[0:1]
	ds_read_b128 v[190:193], v141 offset:16384
	ds_read_b128 v[194:197], v141 offset:17408
	ds_read_b128 v[198:201], v141 offset:18432
	ds_read_b128 v[202:205], v141 offset:19456
	ds_read_b128 v[206:209], v141 offset:20480
	ds_read_b128 v[232:235], v141 offset:21504
	ds_read_b128 v[236:239], v141 offset:22528
	ds_read_b128 v[240:243], v141 offset:23552
	global_load_lds_dwordx4 v[136:137], off
	v_lshl_add_u64 v[210:211], s[36:37], 0, v[134:135]
	s_mov_b32 m0, s82
	v_lshl_add_u64 v[220:221], s[38:39], 0, v[0:1]
	global_load_lds_dwordx4 v[210:211], off
	s_mov_b32 m0, s96
	v_lshl_add_u64 v[222:223], s[34:35], 0, v[132:133]
	global_load_lds_dwordx4 v[220:221], off
	v_lshl_add_u64 v[220:221], s[38:39], 0, v[134:135]
	s_mov_b32 m0, s83
	s_nop 0
	global_load_lds_dwordx4 v[220:221], off
	v_lshl_add_u64 v[220:221], s[34:35], 0, v[130:131]
	s_mov_b32 m0, s19
	s_nop 0
	global_load_lds_dwordx4 v[220:221], off
	s_mov_b32 m0, s54
	s_nop 0
	global_load_lds_dwordx4 v[222:223], off
	s_waitcnt vmcnt(8)
	s_waitcnt lgkmcnt(0)
	s_barrier
	s_setprio 1
	v_mfma_f32_16x16x32_bf16 v[62:65], v[142:145], v[190:193], v[62:65]
	v_mfma_f32_16x16x32_bf16 v[58:61], v[166:169], v[190:193], v[58:61]
	v_mfma_f32_16x16x32_bf16 v[54:57], v[142:145], v[198:201], v[54:57]
	v_mfma_f32_16x16x32_bf16 v[46:49], v[166:169], v[198:201], v[46:49]
	v_mfma_f32_16x16x32_bf16 v[38:41], v[142:145], v[206:209], v[38:41]
	v_mfma_f32_16x16x32_bf16 v[30:33], v[166:169], v[206:209], v[30:33]
	v_mfma_f32_16x16x32_bf16 v[22:25], v[142:145], v[236:239], v[22:25]
	v_mfma_f32_16x16x32_bf16 v[14:17], v[166:169], v[236:239], v[14:17]
	v_mfma_f32_16x16x32_bf16 v[62:65], v[162:165], v[194:197], v[62:65]
	v_mfma_f32_16x16x32_bf16 v[58:61], v[170:173], v[194:197], v[58:61]
	v_mfma_f32_16x16x32_bf16 v[54:57], v[162:165], v[202:205], v[54:57]
	v_mfma_f32_16x16x32_bf16 v[46:49], v[170:173], v[202:205], v[46:49]
	v_mfma_f32_16x16x32_bf16 v[38:41], v[162:165], v[232:235], v[38:41]
	v_mfma_f32_16x16x32_bf16 v[30:33], v[170:173], v[232:235], v[30:33]
	v_mfma_f32_16x16x32_bf16 v[22:25], v[162:165], v[240:243], v[22:25]
	v_mfma_f32_16x16x32_bf16 v[14:17], v[170:173], v[240:243], v[14:17]
	v_mfma_f32_16x16x32_bf16 v[50:53], v[174:177], v[190:193], v[50:53]
	v_mfma_f32_16x16x32_bf16 v[42:45], v[182:185], v[190:193], v[42:45]
	v_mfma_f32_16x16x32_bf16 v[34:37], v[174:177], v[198:201], v[34:37]
	v_mfma_f32_16x16x32_bf16 v[26:29], v[182:185], v[198:201], v[26:29]
	v_mfma_f32_16x16x32_bf16 v[18:21], v[174:177], v[206:209], v[18:21]
	v_mfma_f32_16x16x32_bf16 v[10:13], v[182:185], v[206:209], v[10:13]
	v_mfma_f32_16x16x32_bf16 v[6:9], v[174:177], v[236:239], v[6:9]
	v_mfma_f32_16x16x32_bf16 v[2:5], v[182:185], v[236:239], v[2:5]
	v_mfma_f32_16x16x32_bf16 v[50:53], v[178:181], v[194:197], v[50:53]
	v_mfma_f32_16x16x32_bf16 v[42:45], v[186:189], v[194:197], v[42:45]
	v_mfma_f32_16x16x32_bf16 v[34:37], v[178:181], v[202:205], v[34:37]
	v_mfma_f32_16x16x32_bf16 v[26:29], v[186:189], v[202:205], v[26:29]
	v_mfma_f32_16x16x32_bf16 v[18:21], v[178:181], v[232:235], v[18:21]
	v_mfma_f32_16x16x32_bf16 v[10:13], v[186:189], v[232:235], v[10:13]
	v_mfma_f32_16x16x32_bf16 v[6:9], v[178:181], v[240:243], v[6:9]
	v_mfma_f32_16x16x32_bf16 v[2:5], v[186:189], v[240:243], v[2:5]
	s_setprio 0
	s_barrier
	v_add_u32_e32 v146, s81, v139
	ds_read_b128 v[142:145], v146
	ds_read_b128 v[162:165], v146 offset:1024
	ds_read_b128 v[166:169], v146 offset:2048
	ds_read_b128 v[170:173], v146 offset:3072
	v_add_u32_e32 v146, s80, v139
	ds_read_b128 v[174:177], v146
	ds_read_b128 v[178:181], v146 offset:1024
	ds_read_b128 v[182:185], v146 offset:2048
	ds_read_b128 v[186:189], v146 offset:3072
	s_mov_b32 m0, s55
	v_lshl_add_u64 v[244:245], s[30:31], 0, v[130:131]
	ds_read_b128 v[190:193], v141 offset:32768
	ds_read_b128 v[194:197], v141 offset:33792
	ds_read_b128 v[198:201], v141 offset:34816
	ds_read_b128 v[202:205], v141 offset:35840
	ds_read_b128 v[206:209], v141 offset:36864
	ds_read_b128 v[232:235], v141 offset:37888
	ds_read_b128 v[236:239], v141 offset:38912
	ds_read_b128 v[240:243], v141 offset:39936
	global_load_lds_dwordx4 v[244:245], off
	v_lshl_add_u64 v[244:245], s[30:31], 0, v[132:133]
	s_mov_b32 m0, s70
	s_nop 0
	global_load_lds_dwordx4 v[244:245], off
	s_waitcnt vmcnt(8)
	s_waitcnt lgkmcnt(0)
	s_barrier
	s_setprio 1
	v_mfma_f32_16x16x32_bf16 v[126:129], v[142:145], v[190:193], v[126:129]
	v_mfma_f32_16x16x32_bf16 v[122:125], v[166:169], v[190:193], v[122:125]
	v_mfma_f32_16x16x32_bf16 v[118:121], v[142:145], v[198:201], v[118:121]
	v_mfma_f32_16x16x32_bf16 v[110:113], v[166:169], v[198:201], v[110:113]
	v_mfma_f32_16x16x32_bf16 v[102:105], v[142:145], v[206:209], v[102:105]
	v_mfma_f32_16x16x32_bf16 v[94:97], v[166:169], v[206:209], v[94:97]
	v_mfma_f32_16x16x32_bf16 v[86:89], v[142:145], v[236:239], v[86:89]
	v_mfma_f32_16x16x32_bf16 v[78:81], v[166:169], v[236:239], v[78:81]
	v_mfma_f32_16x16x32_bf16 v[126:129], v[162:165], v[194:197], v[126:129]
	v_mfma_f32_16x16x32_bf16 v[122:125], v[170:173], v[194:197], v[122:125]
	v_mfma_f32_16x16x32_bf16 v[118:121], v[162:165], v[202:205], v[118:121]
	v_mfma_f32_16x16x32_bf16 v[110:113], v[170:173], v[202:205], v[110:113]
	v_mfma_f32_16x16x32_bf16 v[102:105], v[162:165], v[232:235], v[102:105]
	v_mfma_f32_16x16x32_bf16 v[94:97], v[170:173], v[232:235], v[94:97]
	v_mfma_f32_16x16x32_bf16 v[86:89], v[162:165], v[240:243], v[86:89]
	v_mfma_f32_16x16x32_bf16 v[78:81], v[170:173], v[240:243], v[78:81]
	v_mfma_f32_16x16x32_bf16 v[114:117], v[174:177], v[190:193], v[114:117]
	v_mfma_f32_16x16x32_bf16 v[106:109], v[182:185], v[190:193], v[106:109]
	v_mfma_f32_16x16x32_bf16 v[98:101], v[174:177], v[198:201], v[98:101]
	v_mfma_f32_16x16x32_bf16 v[90:93], v[182:185], v[198:201], v[90:93]
	v_mfma_f32_16x16x32_bf16 v[82:85], v[174:177], v[206:209], v[82:85]
	v_mfma_f32_16x16x32_bf16 v[74:77], v[182:185], v[206:209], v[74:77]
	v_mfma_f32_16x16x32_bf16 v[70:73], v[174:177], v[236:239], v[70:73]
	v_mfma_f32_16x16x32_bf16 v[66:69], v[182:185], v[236:239], v[66:69]
	v_mfma_f32_16x16x32_bf16 v[114:117], v[178:181], v[194:197], v[114:117]
	v_mfma_f32_16x16x32_bf16 v[106:109], v[186:189], v[194:197], v[106:109]
	v_mfma_f32_16x16x32_bf16 v[98:101], v[178:181], v[202:205], v[98:101]
	v_mfma_f32_16x16x32_bf16 v[90:93], v[186:189], v[202:205], v[90:93]
	v_mfma_f32_16x16x32_bf16 v[82:85], v[178:181], v[232:235], v[82:85]
	v_mfma_f32_16x16x32_bf16 v[74:77], v[186:189], v[232:235], v[74:77]
	v_mfma_f32_16x16x32_bf16 v[70:73], v[178:181], v[240:243], v[70:73]
	v_mfma_f32_16x16x32_bf16 v[66:69], v[186:189], v[240:243], v[66:69]
	s_setprio 0
	s_barrier
	s_mov_b32 m0, s79
	v_lshl_add_u64 v[136:137], v[136:137], 0, s[90:91]
	ds_read_b128 v[190:193], v141 offset:49152
	ds_read_b128 v[194:197], v141 offset:50176
	ds_read_b128 v[198:201], v141 offset:51200
	ds_read_b128 v[202:205], v141 offset:52224
	ds_read_b128 v[206:209], v141 offset:53248
	ds_read_b128 v[232:235], v141 offset:54272
	ds_read_b128 v[236:239], v141 offset:55296
	ds_read_b128 v[240:243], v141 offset:56320
	global_load_lds_dwordx4 v[136:137], off
	v_lshl_add_u64 v[136:137], v[210:211], 0, s[90:91]
	s_mov_b32 m0, s78
	s_nop 0
	global_load_lds_dwordx4 v[136:137], off
	v_lshl_add_u64 v[136:137], s[28:29], 0, v[0:1]
	s_mov_b32 m0, vcc_hi
	s_nop 0
	global_load_lds_dwordx4 v[136:137], off
	v_lshl_add_u64 v[136:137], s[28:29], 0, v[134:135]
	s_mov_b32 m0, s56
	s_nop 0
	global_load_lds_dwordx4 v[136:137], off
	v_lshl_add_u64 v[136:137], v[220:221], 0, s[90:91]
	s_mov_b32 m0, s71
	s_nop 0
	global_load_lds_dwordx4 v[136:137], off
	v_lshl_add_u64 v[136:137], v[222:223], 0, s[90:91]
	s_mov_b32 m0, s72
	s_nop 0
	global_load_lds_dwordx4 v[136:137], off
	s_waitcnt vmcnt(8)
	s_waitcnt lgkmcnt(0)
	s_barrier
	s_setprio 1
	v_mfma_f32_16x16x32_bf16 v[62:65], v[142:145], v[190:193], v[62:65]
	v_mfma_f32_16x16x32_bf16 v[58:61], v[166:169], v[190:193], v[58:61]
	v_mfma_f32_16x16x32_bf16 v[54:57], v[142:145], v[198:201], v[54:57]
	v_mfma_f32_16x16x32_bf16 v[46:49], v[166:169], v[198:201], v[46:49]
	v_mfma_f32_16x16x32_bf16 v[38:41], v[142:145], v[206:209], v[38:41]
	v_mfma_f32_16x16x32_bf16 v[30:33], v[166:169], v[206:209], v[30:33]
	v_mfma_f32_16x16x32_bf16 v[22:25], v[142:145], v[236:239], v[22:25]
	v_mfma_f32_16x16x32_bf16 v[14:17], v[166:169], v[236:239], v[14:17]
	v_mfma_f32_16x16x32_bf16 v[62:65], v[162:165], v[194:197], v[62:65]
	v_mfma_f32_16x16x32_bf16 v[58:61], v[170:173], v[194:197], v[58:61]
	v_mfma_f32_16x16x32_bf16 v[54:57], v[162:165], v[202:205], v[54:57]
	v_mfma_f32_16x16x32_bf16 v[46:49], v[170:173], v[202:205], v[46:49]
	v_mfma_f32_16x16x32_bf16 v[38:41], v[162:165], v[232:235], v[38:41]
	v_mfma_f32_16x16x32_bf16 v[30:33], v[170:173], v[232:235], v[30:33]
	v_mfma_f32_16x16x32_bf16 v[22:25], v[162:165], v[240:243], v[22:25]
	v_mfma_f32_16x16x32_bf16 v[14:17], v[170:173], v[240:243], v[14:17]
	v_mfma_f32_16x16x32_bf16 v[50:53], v[174:177], v[190:193], v[50:53]
	v_mfma_f32_16x16x32_bf16 v[42:45], v[182:185], v[190:193], v[42:45]
	v_mfma_f32_16x16x32_bf16 v[34:37], v[174:177], v[198:201], v[34:37]
	v_mfma_f32_16x16x32_bf16 v[26:29], v[182:185], v[198:201], v[26:29]
	v_mfma_f32_16x16x32_bf16 v[18:21], v[174:177], v[206:209], v[18:21]
	v_mfma_f32_16x16x32_bf16 v[10:13], v[182:185], v[206:209], v[10:13]
	v_mfma_f32_16x16x32_bf16 v[6:9], v[174:177], v[236:239], v[6:9]
	v_mfma_f32_16x16x32_bf16 v[2:5], v[182:185], v[236:239], v[2:5]
	v_mfma_f32_16x16x32_bf16 v[50:53], v[178:181], v[194:197], v[50:53]
	v_mfma_f32_16x16x32_bf16 v[42:45], v[186:189], v[194:197], v[42:45]
	v_mfma_f32_16x16x32_bf16 v[34:37], v[178:181], v[202:205], v[34:37]
	v_mfma_f32_16x16x32_bf16 v[26:29], v[186:189], v[202:205], v[26:29]
	v_mfma_f32_16x16x32_bf16 v[18:21], v[178:181], v[232:235], v[18:21]
	v_mfma_f32_16x16x32_bf16 v[10:13], v[186:189], v[232:235], v[10:13]
	v_mfma_f32_16x16x32_bf16 v[6:9], v[178:181], v[240:243], v[6:9]
	v_mfma_f32_16x16x32_bf16 v[2:5], v[186:189], v[240:243], v[2:5]
	s_setprio 0
	s_barrier
	s_movk_i32 s30, 0x100
	s_andn2_b64 vcc, exec, s[26:27]
	s_mov_b64 s[28:29], -1
	s_mov_b64 s[26:27], 0
	s_cbranch_vccz .LBB0_570
	s_and_b64 vcc, exec, s[10:11]
	s_cbranch_vccz .LBB0_573
	s_barrier

.LBB0_586:
	s_ashr_i32 s13, s12, 31
	s_lshl_b64 s[16:17], s[12:13], 17
	s_add_u32 s16, s30, s16
	v_cmp_lt_i64_e32 vcc, s[6:7], v[152:153]
	s_addc_u32 s17, s31, s17
	s_and_b64 s[18:19], vcc, exec
	s_cselect_b32 s27, s17, s21
	s_cselect_b32 s26, s16, s20
	s_ashr_i32 s11, s10, 31
	s_lshl_b64 s[18:19], s[10:11], 17
	s_add_u32 s18, s34, s18
	s_addc_u32 s19, s35, s19
	s_and_b64 s[24:25], vcc, exec
	s_cselect_b32 s25, s19, s23
	s_cselect_b32 s24, s18, s22
	s_add_i32 s13, 0, 0x10000
	s_add_i32 s45, 0, 0x14000
	v_add_u32_e32 v146, s13, v43
	v_add_u32_e32 v160, s45, v43
	ds_read_b128 v[2:5], v146
	ds_read_b128 v[6:9], v146 offset:1024
	ds_read_b128 v[10:13], v146 offset:2048
	ds_read_b128 v[14:17], v146 offset:3072
	ds_read_b128 v[18:21], v160
	ds_read_b128 v[22:25], v160 offset:1024
	ds_read_b128 v[26:29], v160 offset:2048
	ds_read_b128 v[30:33], v160 offset:3072
	s_add_u32 s46, s20, 0x10080
	s_addc_u32 s47, s21, 0
	s_add_i32 s53, s15, 0xc000
	v_lshl_add_u64 v[40:41], s[46:47], 0, v[34:35]
	s_mov_b32 m0, s53
	s_add_i32 s11, s15, 0xe000
	ds_read_b128 v[46:49], v45
	ds_read_b128 v[50:53], v45 offset:1024
	ds_read_b128 v[54:57], v45 offset:2048
	ds_read_b128 v[58:61], v45 offset:3072
	ds_read_b128 v[62:65], v45 offset:4096
	ds_read_b128 v[66:69], v45 offset:5120
	ds_read_b128 v[70:73], v45 offset:6144
	ds_read_b128 v[74:77], v45 offset:7168
	global_load_lds_dwordx4 v[40:41], off
	v_lshl_add_u64 v[40:41], s[46:47], 0, v[36:37]
	s_mov_b32 m0, s11
	s_nop 0
	global_load_lds_dwordx4 v[40:41], off
	s_waitcnt vmcnt(8)
	s_waitcnt lgkmcnt(0)
	s_barrier
	s_setprio 1
	v_mfma_f32_16x16x32_bf16 v[78:81], v[2:5], v[46:49], 0
	v_mfma_f32_16x16x32_bf16 v[82:85], v[10:13], v[46:49], 0
	v_mfma_f32_16x16x32_bf16 v[86:89], v[2:5], v[54:57], 0
	v_mfma_f32_16x16x32_bf16 v[90:93], v[10:13], v[54:57], 0
	v_mfma_f32_16x16x32_bf16 v[94:97], v[2:5], v[62:65], 0
	v_mfma_f32_16x16x32_bf16 v[98:101], v[10:13], v[62:65], 0
	v_mfma_f32_16x16x32_bf16 v[102:105], v[2:5], v[70:73], 0
	v_mfma_f32_16x16x32_bf16 v[106:109], v[10:13], v[70:73], 0
	v_mfma_f32_16x16x32_bf16 v[78:81], v[6:9], v[50:53], v[78:81]
	v_mfma_f32_16x16x32_bf16 v[82:85], v[14:17], v[50:53], v[82:85]
	v_mfma_f32_16x16x32_bf16 v[86:89], v[6:9], v[58:61], v[86:89]
	v_mfma_f32_16x16x32_bf16 v[90:93], v[14:17], v[58:61], v[90:93]
	v_mfma_f32_16x16x32_bf16 v[94:97], v[6:9], v[66:69], v[94:97]
	v_mfma_f32_16x16x32_bf16 v[98:101], v[14:17], v[66:69], v[98:101]
	v_mfma_f32_16x16x32_bf16 v[102:105], v[6:9], v[74:77], v[102:105]
	v_mfma_f32_16x16x32_bf16 v[106:109], v[14:17], v[74:77], v[106:109]
	v_mfma_f32_16x16x32_bf16 v[110:113], v[18:21], v[46:49], 0
	v_mfma_f32_16x16x32_bf16 v[46:49], v[26:29], v[46:49], 0
	v_mfma_f32_16x16x32_bf16 v[110:113], v[22:25], v[50:53], v[110:113]
	v_mfma_f32_16x16x32_bf16 v[46:49], v[30:33], v[50:53], v[46:49]
	v_mfma_f32_16x16x32_bf16 v[50:53], v[18:21], v[54:57], 0
	v_mfma_f32_16x16x32_bf16 v[54:57], v[26:29], v[54:57], 0
	v_mfma_f32_16x16x32_bf16 v[50:53], v[22:25], v[58:61], v[50:53]
	v_mfma_f32_16x16x32_bf16 v[54:57], v[30:33], v[58:61], v[54:57]
	v_mfma_f32_16x16x32_bf16 v[58:61], v[18:21], v[62:65], 0
	v_mfma_f32_16x16x32_bf16 v[62:65], v[26:29], v[62:65], 0
	v_mfma_f32_16x16x32_bf16 v[58:61], v[22:25], v[66:69], v[58:61]
	v_mfma_f32_16x16x32_bf16 v[62:65], v[30:33], v[66:69], v[62:65]
	v_mfma_f32_16x16x32_bf16 v[66:69], v[18:21], v[70:73], 0
	v_mfma_f32_16x16x32_bf16 v[70:73], v[26:29], v[70:73], 0
	v_mfma_f32_16x16x32_bf16 v[66:69], v[22:25], v[74:77], v[66:69]
	v_mfma_f32_16x16x32_bf16 v[70:73], v[30:33], v[74:77], v[70:73]
	s_setprio 0
	s_barrier
	s_add_i32 s47, s13, s36
	v_lshl_add_u64 v[40:41], s[22:23], 0, v[0:1]
	s_mov_b64 s[56:57], 0x100
	s_add_i32 s13, s47, 0x2000
	v_lshl_add_u64 v[142:143], v[40:41], 0, s[56:57]
	s_mov_b32 m0, s47
	v_lshl_add_u64 v[210:211], s[22:23], 0, v[38:39]
	s_add_u32 s54, s22, 0x10100
	ds_read_b128 v[74:77], v45 offset:16384
	ds_read_b128 v[114:117], v45 offset:17408
	ds_read_b128 v[118:121], v45 offset:18432
	ds_read_b128 v[122:125], v45 offset:19456
	ds_read_b128 v[126:129], v45 offset:20480
	ds_read_b128 v[130:133], v45 offset:21504
	ds_read_b128 v[134:137], v45 offset:22528
	ds_read_b128 v[138:141], v45 offset:23552
	global_load_lds_dwordx4 v[142:143], off
	v_lshl_add_u64 v[142:143], v[210:211], 0, s[56:57]
	s_mov_b32 m0, s13
	s_addc_u32 s55, s23, 0
	s_add_i32 s45, s45, s36
	global_load_lds_dwordx4 v[142:143], off
	v_lshl_add_u64 v[142:143], s[54:55], 0, v[0:1]
	s_mov_b32 m0, s45
	s_add_i32 s46, s45, 0x2000
	global_load_lds_dwordx4 v[142:143], off
	v_lshl_add_u64 v[142:143], s[54:55], 0, v[38:39]
	s_mov_b32 m0, s46
	v_lshl_add_u64 v[220:221], s[20:21], 0, v[34:35]
	global_load_lds_dwordx4 v[142:143], off
	v_lshl_add_u64 v[142:143], v[220:221], 0, s[56:57]
	s_mov_b32 m0, s15
	v_lshl_add_u64 v[222:223], s[20:21], 0, v[36:37]
	global_load_lds_dwordx4 v[142:143], off
	v_lshl_add_u64 v[142:143], v[222:223], 0, s[56:57]
	s_mov_b32 m0, s37
	s_nop 0
	global_load_lds_dwordx4 v[142:143], off
	s_waitcnt vmcnt(8)
	s_waitcnt lgkmcnt(0)
	s_barrier
	s_setprio 1
	v_mfma_f32_16x16x32_bf16 v[142:145], v[2:5], v[74:77], 0
	v_mfma_f32_16x16x32_bf16 v[166:169], v[2:5], v[118:121], 0
	v_mfma_f32_16x16x32_bf16 v[174:177], v[2:5], v[126:129], 0
	v_mfma_f32_16x16x32_bf16 v[2:5], v[2:5], v[134:137], 0
	v_mfma_f32_16x16x32_bf16 v[142:145], v[6:9], v[114:117], v[142:145]
	v_mfma_f32_16x16x32_bf16 v[162:165], v[10:13], v[74:77], 0
	v_mfma_f32_16x16x32_bf16 v[166:169], v[6:9], v[122:125], v[166:169]
	v_mfma_f32_16x16x32_bf16 v[170:173], v[10:13], v[118:121], 0
	v_mfma_f32_16x16x32_bf16 v[174:177], v[6:9], v[130:133], v[174:177]
	v_mfma_f32_16x16x32_bf16 v[178:181], v[10:13], v[126:129], 0
	v_mfma_f32_16x16x32_bf16 v[2:5], v[6:9], v[138:141], v[2:5]
	v_mfma_f32_16x16x32_bf16 v[6:9], v[10:13], v[134:137], 0
	v_mfma_f32_16x16x32_bf16 v[162:165], v[14:17], v[114:117], v[162:165]
	v_mfma_f32_16x16x32_bf16 v[170:173], v[14:17], v[122:125], v[170:173]
	v_mfma_f32_16x16x32_bf16 v[178:181], v[14:17], v[130:133], v[178:181]
	v_mfma_f32_16x16x32_bf16 v[6:9], v[14:17], v[138:141], v[6:9]
	v_mfma_f32_16x16x32_bf16 v[10:13], v[18:21], v[74:77], 0
	v_mfma_f32_16x16x32_bf16 v[14:17], v[26:29], v[74:77], 0
	v_mfma_f32_16x16x32_bf16 v[10:13], v[22:25], v[114:117], v[10:13]
	v_mfma_f32_16x16x32_bf16 v[14:17], v[30:33], v[114:117], v[14:17]
	v_mfma_f32_16x16x32_bf16 v[74:77], v[18:21], v[118:121], 0
	v_mfma_f32_16x16x32_bf16 v[114:117], v[26:29], v[118:121], 0
	v_mfma_f32_16x16x32_bf16 v[118:121], v[18:21], v[126:129], 0
	v_mfma_f32_16x16x32_bf16 v[18:21], v[18:21], v[134:137], 0
	v_mfma_f32_16x16x32_bf16 v[74:77], v[22:25], v[122:125], v[74:77]
	v_mfma_f32_16x16x32_bf16 v[114:117], v[30:33], v[122:125], v[114:117]
	v_mfma_f32_16x16x32_bf16 v[118:121], v[22:25], v[130:133], v[118:121]
	v_mfma_f32_16x16x32_bf16 v[122:125], v[26:29], v[126:129], 0
	v_mfma_f32_16x16x32_bf16 v[18:21], v[22:25], v[138:141], v[18:21]
	v_mfma_f32_16x16x32_bf16 v[22:25], v[26:29], v[134:137], 0
	v_mfma_f32_16x16x32_bf16 v[122:125], v[30:33], v[130:133], v[122:125]
	v_mfma_f32_16x16x32_bf16 v[22:25], v[30:33], v[138:141], v[22:25]
	s_setprio 0
	s_barrier
	s_add_i32 s52, 0, 0x18000
	s_add_i32 s70, 0, 0x1c000
	v_add_u32_e32 v231, s52, v43
	v_add_u32_e32 v246, s70, v43
	ds_read_b128 v[26:29], v231
	ds_read_b128 v[30:33], v231 offset:1024
	ds_read_b128 v[126:129], v231 offset:2048
	ds_read_b128 v[130:133], v231 offset:3072
	ds_read_b128 v[134:137], v246
	ds_read_b128 v[138:141], v246 offset:1024
	ds_read_b128 v[182:185], v246 offset:2048
	ds_read_b128 v[186:189], v246 offset:3072
	s_add_u32 s54, s20, 0x10100
	s_addc_u32 s55, s21, 0
	s_mov_b32 m0, s38
	v_lshl_add_u64 v[244:245], s[54:55], 0, v[34:35]
	ds_read_b128 v[190:193], v45 offset:32768
	ds_read_b128 v[194:197], v45 offset:33792
	ds_read_b128 v[198:201], v45 offset:34816
	ds_read_b128 v[202:205], v45 offset:35840
	ds_read_b128 v[206:209], v45 offset:36864
	ds_read_b128 v[232:235], v45 offset:37888
	ds_read_b128 v[236:239], v45 offset:38912
	ds_read_b128 v[240:243], v45 offset:39936
	global_load_lds_dwordx4 v[244:245], off
	v_lshl_add_u64 v[244:245], s[54:55], 0, v[36:37]
	s_mov_b32 m0, s39
	s_nop 0
	global_load_lds_dwordx4 v[244:245], off
	s_waitcnt vmcnt(8)
	s_waitcnt lgkmcnt(0)
	s_barrier
	s_setprio 1
	v_mfma_f32_16x16x32_bf16 v[78:81], v[26:29], v[190:193], v[78:81]
	v_mfma_f32_16x16x32_bf16 v[82:85], v[126:129], v[190:193], v[82:85]
	v_mfma_f32_16x16x32_bf16 v[86:89], v[26:29], v[198:201], v[86:89]
	v_mfma_f32_16x16x32_bf16 v[90:93], v[126:129], v[198:201], v[90:93]
	v_mfma_f32_16x16x32_bf16 v[94:97], v[26:29], v[206:209], v[94:97]
	v_mfma_f32_16x16x32_bf16 v[98:101], v[126:129], v[206:209], v[98:101]
	v_mfma_f32_16x16x32_bf16 v[102:105], v[26:29], v[236:239], v[102:105]
	v_mfma_f32_16x16x32_bf16 v[106:109], v[126:129], v[236:239], v[106:109]
	v_mfma_f32_16x16x32_bf16 v[78:81], v[30:33], v[194:197], v[78:81]
	v_mfma_f32_16x16x32_bf16 v[82:85], v[130:133], v[194:197], v[82:85]
	v_mfma_f32_16x16x32_bf16 v[86:89], v[30:33], v[202:205], v[86:89]
	v_mfma_f32_16x16x32_bf16 v[90:93], v[130:133], v[202:205], v[90:93]
	v_mfma_f32_16x16x32_bf16 v[94:97], v[30:33], v[232:235], v[94:97]
	v_mfma_f32_16x16x32_bf16 v[98:101], v[130:133], v[232:235], v[98:101]
	v_mfma_f32_16x16x32_bf16 v[102:105], v[30:33], v[240:243], v[102:105]
	v_mfma_f32_16x16x32_bf16 v[106:109], v[130:133], v[240:243], v[106:109]
	v_mfma_f32_16x16x32_bf16 v[110:113], v[134:137], v[190:193], v[110:113]
	v_mfma_f32_16x16x32_bf16 v[46:49], v[182:185], v[190:193], v[46:49]
	v_mfma_f32_16x16x32_bf16 v[50:53], v[134:137], v[198:201], v[50:53]
	v_mfma_f32_16x16x32_bf16 v[54:57], v[182:185], v[198:201], v[54:57]
	v_mfma_f32_16x16x32_bf16 v[58:61], v[134:137], v[206:209], v[58:61]
	v_mfma_f32_16x16x32_bf16 v[62:65], v[182:185], v[206:209], v[62:65]
	v_mfma_f32_16x16x32_bf16 v[66:69], v[134:137], v[236:239], v[66:69]
	v_mfma_f32_16x16x32_bf16 v[70:73], v[182:185], v[236:239], v[70:73]
	v_mfma_f32_16x16x32_bf16 v[110:113], v[138:141], v[194:197], v[110:113]
	v_mfma_f32_16x16x32_bf16 v[46:49], v[186:189], v[194:197], v[46:49]
	v_mfma_f32_16x16x32_bf16 v[50:53], v[138:141], v[202:205], v[50:53]
	v_mfma_f32_16x16x32_bf16 v[54:57], v[186:189], v[202:205], v[54:57]
	v_mfma_f32_16x16x32_bf16 v[58:61], v[138:141], v[232:235], v[58:61]
	v_mfma_f32_16x16x32_bf16 v[62:65], v[186:189], v[232:235], v[62:65]
	v_mfma_f32_16x16x32_bf16 v[66:69], v[138:141], v[240:243], v[66:69]
	v_mfma_f32_16x16x32_bf16 v[70:73], v[186:189], v[240:243], v[70:73]
	s_setprio 0
	s_barrier
	s_add_i32 s54, s52, s36
	s_mov_b64 s[76:77], 0x180
	s_add_i32 s52, s54, 0x2000
	v_lshl_add_u64 v[40:41], v[40:41], 0, s[76:77]
	s_mov_b32 m0, s54
	s_add_u32 s56, s22, 0x10180
	ds_read_b128 v[190:193], v45 offset:49152
	ds_read_b128 v[194:197], v45 offset:50176
	ds_read_b128 v[198:201], v45 offset:51200
	ds_read_b128 v[202:205], v45 offset:52224
	ds_read_b128 v[206:209], v45 offset:53248
	ds_read_b128 v[232:235], v45 offset:54272
	ds_read_b128 v[236:239], v45 offset:55296
	ds_read_b128 v[240:243], v45 offset:56320
	global_load_lds_dwordx4 v[40:41], off
	v_lshl_add_u64 v[40:41], v[210:211], 0, s[76:77]
	s_mov_b32 m0, s52
	s_addc_u32 s57, s23, 0
	s_add_i32 s22, s70, s36
	global_load_lds_dwordx4 v[40:41], off
	v_lshl_add_u64 v[40:41], s[56:57], 0, v[0:1]
	s_mov_b32 m0, s22
	s_add_i32 s23, s22, 0x2000
	global_load_lds_dwordx4 v[40:41], off
	v_lshl_add_u64 v[40:41], s[56:57], 0, v[38:39]
	s_mov_b32 m0, s23
	s_nop 0
	global_load_lds_dwordx4 v[40:41], off
	v_lshl_add_u64 v[40:41], v[220:221], 0, s[76:77]
	s_mov_b32 m0, s40
	s_nop 0
	global_load_lds_dwordx4 v[40:41], off
	v_lshl_add_u64 v[40:41], v[222:223], 0, s[76:77]
	s_mov_b32 m0, s41
	s_nop 0
	global_load_lds_dwordx4 v[40:41], off
	s_waitcnt vmcnt(8)
	s_waitcnt lgkmcnt(0)
	s_barrier
	s_setprio 1
	v_mfma_f32_16x16x32_bf16 v[142:145], v[26:29], v[190:193], v[142:145]
	v_mfma_f32_16x16x32_bf16 v[162:165], v[126:129], v[190:193], v[162:165]
	v_mfma_f32_16x16x32_bf16 v[166:169], v[26:29], v[198:201], v[166:169]
	v_mfma_f32_16x16x32_bf16 v[170:173], v[126:129], v[198:201], v[170:173]
	v_mfma_f32_16x16x32_bf16 v[174:177], v[26:29], v[206:209], v[174:177]
	v_mfma_f32_16x16x32_bf16 v[178:181], v[126:129], v[206:209], v[178:181]
	v_mfma_f32_16x16x32_bf16 v[2:5], v[26:29], v[236:239], v[2:5]
	v_mfma_f32_16x16x32_bf16 v[6:9], v[126:129], v[236:239], v[6:9]
	v_mfma_f32_16x16x32_bf16 v[142:145], v[30:33], v[194:197], v[142:145]
	v_mfma_f32_16x16x32_bf16 v[162:165], v[130:133], v[194:197], v[162:165]
	v_mfma_f32_16x16x32_bf16 v[166:169], v[30:33], v[202:205], v[166:169]
	v_mfma_f32_16x16x32_bf16 v[170:173], v[130:133], v[202:205], v[170:173]
	v_mfma_f32_16x16x32_bf16 v[174:177], v[30:33], v[232:235], v[174:177]
	v_mfma_f32_16x16x32_bf16 v[178:181], v[130:133], v[232:235], v[178:181]
	v_mfma_f32_16x16x32_bf16 v[2:5], v[30:33], v[240:243], v[2:5]
	v_mfma_f32_16x16x32_bf16 v[6:9], v[130:133], v[240:243], v[6:9]
	v_mfma_f32_16x16x32_bf16 v[10:13], v[134:137], v[190:193], v[10:13]
	v_mfma_f32_16x16x32_bf16 v[14:17], v[182:185], v[190:193], v[14:17]
	v_mfma_f32_16x16x32_bf16 v[26:29], v[134:137], v[198:201], v[74:77]
	v_mfma_f32_16x16x32_bf16 v[30:33], v[182:185], v[198:201], v[114:117]
	v_mfma_f32_16x16x32_bf16 v[74:77], v[134:137], v[206:209], v[118:121]
	v_mfma_f32_16x16x32_bf16 v[114:117], v[182:185], v[206:209], v[122:125]
	v_mfma_f32_16x16x32_bf16 v[18:21], v[134:137], v[236:239], v[18:21]
	v_mfma_f32_16x16x32_bf16 v[22:25], v[182:185], v[236:239], v[22:25]
	v_mfma_f32_16x16x32_bf16 v[10:13], v[138:141], v[194:197], v[10:13]
	v_mfma_f32_16x16x32_bf16 v[14:17], v[186:189], v[194:197], v[14:17]
	v_mfma_f32_16x16x32_bf16 v[26:29], v[138:141], v[202:205], v[26:29]
	v_mfma_f32_16x16x32_bf16 v[30:33], v[186:189], v[202:205], v[30:33]
	v_mfma_f32_16x16x32_bf16 v[74:77], v[138:141], v[232:235], v[74:77]
	v_mfma_f32_16x16x32_bf16 v[114:117], v[186:189], v[232:235], v[114:117]
	v_mfma_f32_16x16x32_bf16 v[18:21], v[138:141], v[240:243], v[18:21]
	v_mfma_f32_16x16x32_bf16 v[22:25], v[186:189], v[240:243], v[22:25]
	s_setprio 0
	s_barrier
	ds_read_b128 v[118:121], v146
	ds_read_b128 v[122:125], v146 offset:1024
	ds_read_b128 v[126:129], v146 offset:2048
	ds_read_b128 v[130:133], v146 offset:3072
	ds_read_b128 v[134:137], v160
	ds_read_b128 v[138:141], v160 offset:1024
	ds_read_b128 v[182:185], v160 offset:2048
	ds_read_b128 v[186:189], v160 offset:3072
	s_add_u32 s20, s20, 0x10180
	s_addc_u32 s21, s21, 0
	s_mov_b32 m0, s53
	v_lshl_add_u64 v[40:41], s[20:21], 0, v[34:35]
	ds_read_b128 v[190:193], v45
	ds_read_b128 v[194:197], v45 offset:1024
	ds_read_b128 v[198:201], v45 offset:2048
	ds_read_b128 v[202:205], v45 offset:3072
	ds_read_b128 v[206:209], v45 offset:4096
	ds_read_b128 v[232:235], v45 offset:5120
	ds_read_b128 v[236:239], v45 offset:6144
	ds_read_b128 v[240:243], v45 offset:7168
	global_load_lds_dwordx4 v[40:41], off
	v_lshl_add_u64 v[40:41], s[20:21], 0, v[36:37]
	s_mov_b32 m0, s11
	s_nop 0
	global_load_lds_dwordx4 v[40:41], off
	s_waitcnt vmcnt(8)
	s_waitcnt lgkmcnt(0)
	s_barrier
	s_setprio 1
	v_mfma_f32_16x16x32_bf16 v[78:81], v[118:121], v[190:193], v[78:81]
	v_mfma_f32_16x16x32_bf16 v[82:85], v[126:129], v[190:193], v[82:85]
	v_mfma_f32_16x16x32_bf16 v[86:89], v[118:121], v[198:201], v[86:89]
	v_mfma_f32_16x16x32_bf16 v[90:93], v[126:129], v[198:201], v[90:93]
	v_mfma_f32_16x16x32_bf16 v[94:97], v[118:121], v[206:209], v[94:97]
	v_mfma_f32_16x16x32_bf16 v[98:101], v[126:129], v[206:209], v[98:101]
	v_mfma_f32_16x16x32_bf16 v[102:105], v[118:121], v[236:239], v[102:105]
	v_mfma_f32_16x16x32_bf16 v[106:109], v[126:129], v[236:239], v[106:109]
	v_mfma_f32_16x16x32_bf16 v[78:81], v[122:125], v[194:197], v[78:81]
	v_mfma_f32_16x16x32_bf16 v[82:85], v[130:133], v[194:197], v[82:85]
	v_mfma_f32_16x16x32_bf16 v[86:89], v[122:125], v[202:205], v[86:89]
	v_mfma_f32_16x16x32_bf16 v[90:93], v[130:133], v[202:205], v[90:93]
	v_mfma_f32_16x16x32_bf16 v[94:97], v[122:125], v[232:235], v[94:97]
	v_mfma_f32_16x16x32_bf16 v[98:101], v[130:133], v[232:235], v[98:101]
	v_mfma_f32_16x16x32_bf16 v[102:105], v[122:125], v[240:243], v[102:105]
	v_mfma_f32_16x16x32_bf16 v[106:109], v[130:133], v[240:243], v[106:109]
	v_mfma_f32_16x16x32_bf16 v[110:113], v[134:137], v[190:193], v[110:113]
	v_mfma_f32_16x16x32_bf16 v[46:49], v[182:185], v[190:193], v[46:49]
	v_mfma_f32_16x16x32_bf16 v[50:53], v[134:137], v[198:201], v[50:53]
	v_mfma_f32_16x16x32_bf16 v[54:57], v[182:185], v[198:201], v[54:57]
	v_mfma_f32_16x16x32_bf16 v[58:61], v[134:137], v[206:209], v[58:61]
	v_mfma_f32_16x16x32_bf16 v[62:65], v[182:185], v[206:209], v[62:65]
	v_mfma_f32_16x16x32_bf16 v[66:69], v[134:137], v[236:239], v[66:69]
	v_mfma_f32_16x16x32_bf16 v[70:73], v[182:185], v[236:239], v[70:73]
	v_mfma_f32_16x16x32_bf16 v[110:113], v[138:141], v[194:197], v[110:113]
	v_mfma_f32_16x16x32_bf16 v[46:49], v[186:189], v[194:197], v[46:49]
	v_mfma_f32_16x16x32_bf16 v[50:53], v[138:141], v[202:205], v[50:53]
	v_mfma_f32_16x16x32_bf16 v[54:57], v[186:189], v[202:205], v[54:57]
	v_mfma_f32_16x16x32_bf16 v[58:61], v[138:141], v[232:235], v[58:61]
	v_mfma_f32_16x16x32_bf16 v[62:65], v[186:189], v[232:235], v[62:65]
	v_mfma_f32_16x16x32_bf16 v[66:69], v[138:141], v[240:243], v[66:69]
	v_mfma_f32_16x16x32_bf16 v[70:73], v[186:189], v[240:243], v[70:73]
	s_setprio 0
	s_barrier
	s_mov_b32 m0, s47
	v_lshl_add_u64 v[40:41], s[24:25], 0, v[0:1]
	s_add_u32 s20, s24, 0x10000
	ds_read_b128 v[190:193], v45 offset:16384
	ds_read_b128 v[194:197], v45 offset:17408
	ds_read_b128 v[198:201], v45 offset:18432
	ds_read_b128 v[202:205], v45 offset:19456
	ds_read_b128 v[206:209], v45 offset:20480
	ds_read_b128 v[232:235], v45 offset:21504
	ds_read_b128 v[236:239], v45 offset:22528
	ds_read_b128 v[240:243], v45 offset:23552
	global_load_lds_dwordx4 v[40:41], off
	v_lshl_add_u64 v[210:211], s[24:25], 0, v[38:39]
	s_mov_b32 m0, s13
	s_addc_u32 s21, s25, 0
	global_load_lds_dwordx4 v[210:211], off
	v_lshl_add_u64 v[220:221], s[20:21], 0, v[0:1]
	s_mov_b32 m0, s45
	v_lshl_add_u64 v[222:223], s[26:27], 0, v[36:37]
	global_load_lds_dwordx4 v[220:221], off
	v_lshl_add_u64 v[220:221], s[20:21], 0, v[38:39]
	s_mov_b32 m0, s46
	s_nop 0
	global_load_lds_dwordx4 v[220:221], off
	v_lshl_add_u64 v[220:221], s[26:27], 0, v[34:35]
	s_mov_b32 m0, s15
	s_nop 0
	global_load_lds_dwordx4 v[220:221], off
	s_mov_b32 m0, s37
	s_nop 0
	global_load_lds_dwordx4 v[222:223], off
	s_waitcnt vmcnt(8)
	s_waitcnt lgkmcnt(0)
	s_barrier
	s_setprio 1
	v_mfma_f32_16x16x32_bf16 v[142:145], v[118:121], v[190:193], v[142:145]
	v_mfma_f32_16x16x32_bf16 v[162:165], v[126:129], v[190:193], v[162:165]
	v_mfma_f32_16x16x32_bf16 v[166:169], v[118:121], v[198:201], v[166:169]
	v_mfma_f32_16x16x32_bf16 v[170:173], v[126:129], v[198:201], v[170:173]
	v_mfma_f32_16x16x32_bf16 v[174:177], v[118:121], v[206:209], v[174:177]
	v_mfma_f32_16x16x32_bf16 v[178:181], v[126:129], v[206:209], v[178:181]
	v_mfma_f32_16x16x32_bf16 v[2:5], v[118:121], v[236:239], v[2:5]
	v_mfma_f32_16x16x32_bf16 v[6:9], v[126:129], v[236:239], v[6:9]
	v_mfma_f32_16x16x32_bf16 v[142:145], v[122:125], v[194:197], v[142:145]
	v_mfma_f32_16x16x32_bf16 v[162:165], v[130:133], v[194:197], v[162:165]
	v_mfma_f32_16x16x32_bf16 v[166:169], v[122:125], v[202:205], v[166:169]
	v_mfma_f32_16x16x32_bf16 v[170:173], v[130:133], v[202:205], v[170:173]
	v_mfma_f32_16x16x32_bf16 v[174:177], v[122:125], v[232:235], v[174:177]
	v_mfma_f32_16x16x32_bf16 v[178:181], v[130:133], v[232:235], v[178:181]
	v_mfma_f32_16x16x32_bf16 v[2:5], v[122:125], v[240:243], v[2:5]
	v_mfma_f32_16x16x32_bf16 v[6:9], v[130:133], v[240:243], v[6:9]
	v_mfma_f32_16x16x32_bf16 v[14:17], v[182:185], v[190:193], v[14:17]
	v_mfma_f32_16x16x32_bf16 v[118:121], v[186:189], v[194:197], v[14:17]
	v_mfma_f32_16x16x32_bf16 v[14:17], v[134:137], v[198:201], v[26:29]
	v_mfma_f32_16x16x32_bf16 v[26:29], v[138:141], v[202:205], v[14:17]
	v_mfma_f32_16x16x32_bf16 v[14:17], v[182:185], v[198:201], v[30:33]
	v_mfma_f32_16x16x32_bf16 v[122:125], v[186:189], v[202:205], v[14:17]
	v_mfma_f32_16x16x32_bf16 v[14:17], v[134:137], v[206:209], v[74:77]
	v_mfma_f32_16x16x32_bf16 v[74:77], v[138:141], v[232:235], v[14:17]
	v_mfma_f32_16x16x32_bf16 v[14:17], v[182:185], v[206:209], v[114:117]
	v_mfma_f32_16x16x32_bf16 v[114:117], v[186:189], v[232:235], v[14:17]
	v_mfma_f32_16x16x32_bf16 v[14:17], v[134:137], v[236:239], v[18:21]
	v_mfma_f32_16x16x32_bf16 v[10:13], v[134:137], v[190:193], v[10:13]
	v_mfma_f32_16x16x32_bf16 v[126:129], v[138:141], v[240:243], v[14:17]
	v_mfma_f32_16x16x32_bf16 v[14:17], v[182:185], v[236:239], v[22:25]
	v_mfma_f32_16x16x32_bf16 v[10:13], v[138:141], v[194:197], v[10:13]
	v_mfma_f32_16x16x32_bf16 v[130:133], v[186:189], v[240:243], v[14:17]
	s_setprio 0
	s_barrier
	s_nop 3
	ds_read_b128 v[14:17], v231
	ds_read_b128 v[18:21], v231 offset:1024
	ds_read_b128 v[134:137], v231 offset:2048
	ds_read_b128 v[138:141], v231 offset:3072
	ds_read_b128 v[182:185], v246
	ds_read_b128 v[186:189], v246 offset:1024
	ds_read_b128 v[190:193], v246 offset:2048
	ds_read_b128 v[194:197], v246 offset:3072
	s_add_u32 s20, s26, 0x10000
	s_addc_u32 s21, s27, 0
	s_mov_b32 m0, s38
	v_lshl_add_u64 v[244:245], s[20:21], 0, v[34:35]
	ds_read_b128 v[22:25], v45 offset:32768
	ds_read_b128 v[30:33], v45 offset:33792
	ds_read_b128 v[198:201], v45 offset:34816
	ds_read_b128 v[202:205], v45 offset:35840
	ds_read_b128 v[206:209], v45 offset:36864
	ds_read_b128 v[232:235], v45 offset:37888
	ds_read_b128 v[236:239], v45 offset:38912
	ds_read_b128 v[240:243], v45 offset:39936
	global_load_lds_dwordx4 v[244:245], off
	v_lshl_add_u64 v[244:245], s[20:21], 0, v[36:37]
	s_mov_b32 m0, s39
	s_nop 0
	global_load_lds_dwordx4 v[244:245], off
	s_waitcnt vmcnt(8)
	s_waitcnt lgkmcnt(0)
	s_barrier
	s_setprio 1
	v_mfma_f32_16x16x32_bf16 v[78:81], v[14:17], v[22:25], v[78:81]
	v_mfma_f32_16x16x32_bf16 v[82:85], v[134:137], v[22:25], v[82:85]
	v_mfma_f32_16x16x32_bf16 v[86:89], v[14:17], v[198:201], v[86:89]
	v_mfma_f32_16x16x32_bf16 v[90:93], v[134:137], v[198:201], v[90:93]
	v_mfma_f32_16x16x32_bf16 v[94:97], v[14:17], v[206:209], v[94:97]
	v_mfma_f32_16x16x32_bf16 v[98:101], v[134:137], v[206:209], v[98:101]
	v_mfma_f32_16x16x32_bf16 v[102:105], v[14:17], v[236:239], v[102:105]
	v_mfma_f32_16x16x32_bf16 v[106:109], v[134:137], v[236:239], v[106:109]
	v_mfma_f32_16x16x32_bf16 v[78:81], v[18:21], v[30:33], v[78:81]
	v_mfma_f32_16x16x32_bf16 v[82:85], v[138:141], v[30:33], v[82:85]
	v_mfma_f32_16x16x32_bf16 v[86:89], v[18:21], v[202:205], v[86:89]
	v_mfma_f32_16x16x32_bf16 v[90:93], v[138:141], v[202:205], v[90:93]
	v_mfma_f32_16x16x32_bf16 v[94:97], v[18:21], v[232:235], v[94:97]
	v_mfma_f32_16x16x32_bf16 v[98:101], v[138:141], v[232:235], v[98:101]
	v_mfma_f32_16x16x32_bf16 v[102:105], v[18:21], v[240:243], v[102:105]
	v_mfma_f32_16x16x32_bf16 v[106:109], v[138:141], v[240:243], v[106:109]
	v_mfma_f32_16x16x32_bf16 v[110:113], v[182:185], v[22:25], v[110:113]
	v_mfma_f32_16x16x32_bf16 v[22:25], v[190:193], v[22:25], v[46:49]
	v_mfma_f32_16x16x32_bf16 v[46:49], v[194:197], v[30:33], v[22:25]
	v_mfma_f32_16x16x32_bf16 v[22:25], v[182:185], v[198:201], v[50:53]
	v_mfma_f32_16x16x32_bf16 v[50:53], v[186:189], v[202:205], v[22:25]
	v_mfma_f32_16x16x32_bf16 v[22:25], v[190:193], v[198:201], v[54:57]
	v_mfma_f32_16x16x32_bf16 v[54:57], v[194:197], v[202:205], v[22:25]
	v_mfma_f32_16x16x32_bf16 v[22:25], v[182:185], v[206:209], v[58:61]
	v_mfma_f32_16x16x32_bf16 v[58:61], v[186:189], v[232:235], v[22:25]
	v_mfma_f32_16x16x32_bf16 v[22:25], v[190:193], v[206:209], v[62:65]
	v_mfma_f32_16x16x32_bf16 v[62:65], v[194:197], v[232:235], v[22:25]
	v_mfma_f32_16x16x32_bf16 v[22:25], v[182:185], v[236:239], v[66:69]
	v_mfma_f32_16x16x32_bf16 v[66:69], v[186:189], v[240:243], v[22:25]
	v_mfma_f32_16x16x32_bf16 v[22:25], v[190:193], v[236:239], v[70:73]
	v_mfma_f32_16x16x32_bf16 v[110:113], v[186:189], v[30:33], v[110:113]
	v_mfma_f32_16x16x32_bf16 v[70:73], v[194:197], v[240:243], v[22:25]
	s_setprio 0
	s_barrier
	s_mov_b32 m0, s54
	s_nop 2
	v_lshl_add_u64 v[22:23], v[40:41], 0, s[90:91]
	s_add_u32 s20, s24, 0x10080
	ds_read_b128 v[198:201], v45 offset:49152
	ds_read_b128 v[202:205], v45 offset:50176
	ds_read_b128 v[206:209], v45 offset:51200
	ds_read_b128 v[232:235], v45 offset:52224
	ds_read_b128 v[236:239], v45 offset:53248
	ds_read_b128 v[240:243], v45 offset:54272
	ds_read_b128 v[244:247], v45 offset:55296
	ds_read_b128 v[248:251], v45 offset:56320
	global_load_lds_dwordx4 v[22:23], off
	v_lshl_add_u64 v[22:23], v[210:211], 0, s[90:91]
	s_mov_b32 m0, s52
	s_addc_u32 s21, s25, 0
	global_load_lds_dwordx4 v[22:23], off
	v_lshl_add_u64 v[22:23], s[20:21], 0, v[0:1]
	s_mov_b32 m0, s22
	s_nop 0
	global_load_lds_dwordx4 v[22:23], off
	v_lshl_add_u64 v[22:23], s[20:21], 0, v[38:39]
	s_mov_b32 m0, s23
	s_nop 0
	global_load_lds_dwordx4 v[22:23], off
	v_lshl_add_u64 v[22:23], v[220:221], 0, s[90:91]
	s_mov_b32 m0, s40
	s_nop 0
	global_load_lds_dwordx4 v[22:23], off
	v_lshl_add_u64 v[22:23], v[222:223], 0, s[90:91]
	s_mov_b32 m0, s41
	s_nop 0
	global_load_lds_dwordx4 v[22:23], off
	s_waitcnt vmcnt(8)
	s_waitcnt lgkmcnt(0)
	s_barrier
	s_setprio 1
	v_mfma_f32_16x16x32_bf16 v[22:25], v[14:17], v[198:201], v[142:145]
	v_mfma_f32_16x16x32_bf16 v[142:145], v[18:21], v[202:205], v[22:25]
	v_mfma_f32_16x16x32_bf16 v[22:25], v[134:137], v[198:201], v[162:165]
	v_mfma_f32_16x16x32_bf16 v[162:165], v[138:141], v[202:205], v[22:25]
	v_mfma_f32_16x16x32_bf16 v[22:25], v[14:17], v[206:209], v[166:169]
	v_mfma_f32_16x16x32_bf16 v[166:169], v[18:21], v[232:235], v[22:25]
	v_mfma_f32_16x16x32_bf16 v[22:25], v[134:137], v[206:209], v[170:173]
	v_mfma_f32_16x16x32_bf16 v[170:173], v[138:141], v[232:235], v[22:25]
	v_mfma_f32_16x16x32_bf16 v[22:25], v[14:17], v[236:239], v[174:177]
	v_mfma_f32_16x16x32_bf16 v[2:5], v[14:17], v[244:247], v[2:5]
	v_mfma_f32_16x16x32_bf16 v[30:33], v[18:21], v[240:243], v[22:25]
	v_mfma_f32_16x16x32_bf16 v[22:25], v[134:137], v[236:239], v[178:181]
	v_mfma_f32_16x16x32_bf16 v[14:17], v[18:21], v[248:251], v[2:5]
	v_mfma_f32_16x16x32_bf16 v[2:5], v[134:137], v[244:247], v[6:9]
	v_mfma_f32_16x16x32_bf16 v[22:25], v[138:141], v[240:243], v[22:25]
	v_mfma_f32_16x16x32_bf16 v[6:9], v[138:141], v[248:251], v[2:5]
	v_mfma_f32_16x16x32_bf16 v[2:5], v[182:185], v[198:201], v[10:13]
	v_mfma_f32_16x16x32_bf16 v[134:137], v[186:189], v[202:205], v[2:5]
	v_mfma_f32_16x16x32_bf16 v[2:5], v[190:193], v[198:201], v[118:121]
	v_mfma_f32_16x16x32_bf16 v[118:121], v[194:197], v[202:205], v[2:5]
	v_mfma_f32_16x16x32_bf16 v[2:5], v[182:185], v[206:209], v[26:29]
	v_mfma_f32_16x16x32_bf16 v[138:141], v[186:189], v[232:235], v[2:5]
	v_mfma_f32_16x16x32_bf16 v[2:5], v[190:193], v[206:209], v[122:125]
	v_mfma_f32_16x16x32_bf16 v[122:125], v[194:197], v[232:235], v[2:5]
	v_mfma_f32_16x16x32_bf16 v[2:5], v[182:185], v[236:239], v[74:77]
	v_mfma_f32_16x16x32_bf16 v[26:29], v[186:189], v[240:243], v[2:5]
	v_mfma_f32_16x16x32_bf16 v[2:5], v[190:193], v[236:239], v[114:117]
	v_mfma_f32_16x16x32_bf16 v[18:21], v[194:197], v[240:243], v[2:5]
	v_mfma_f32_16x16x32_bf16 v[2:5], v[182:185], v[244:247], v[126:129]
	v_mfma_f32_16x16x32_bf16 v[10:13], v[186:189], v[248:251], v[2:5]
	v_mfma_f32_16x16x32_bf16 v[2:5], v[190:193], v[244:247], v[130:133]
	v_mfma_f32_16x16x32_bf16 v[2:5], v[194:197], v[248:251], v[2:5]
	s_setprio 0
	s_barrier
	v_lshl_add_u32 v114, s14, 8, v42
	v_lshl_or_b32 v40, s44, 8, v44
	v_ashrrev_i32_e32 v41, 31, v40
	v_ashrrev_i32_e32 v115, 31, v114
	v_lshl_add_u64 v[116:117], v[40:41], 1, s[8:9]
	v_lshlrev_b64 v[40:41], 16, v[114:115]
	v_lshl_add_u64 v[40:41], v[116:117], 0, v[40:41]
	v_cvt_pk_bf16_f32 v74, v78, v79
	v_cvt_pk_bf16_f32 v75, v80, v81
	v_cvt_pk_bf16_f32 v76, v82, v83
	v_cvt_pk_bf16_f32 v77, v84, v85
	global_store_dwordx4 v[40:41], v[74:77], off
	s_mov_b64 s[20:21], 0x800000
	s_mov_b32 s11, 0x900000
	v_cvt_pk_bf16_f32 v74, v110, v111
	v_cvt_pk_bf16_f32 v75, v112, v113
	v_cvt_pk_bf16_f32 v76, v46, v47
	v_or_b32_e32 v46, 16, v114
	v_ashrrev_i32_e32 v47, 31, v46
	v_lshlrev_b64 v[46:47], 16, v[46:47]
	v_cvt_pk_bf16_f32 v77, v48, v49
	global_store_dwordx4 v[40:41], v[74:77], off offset:256
	s_add_i32 s43, s43, s28
	s_mov_b32 s44, s10
	v_lshl_add_u64 v[74:75], v[116:117], 0, v[46:47]
	v_cvt_pk_bf16_f32 v46, v86, v87
	v_cvt_pk_bf16_f32 v47, v88, v89
	v_cvt_pk_bf16_f32 v48, v90, v91
	v_cvt_pk_bf16_f32 v49, v92, v93
	global_store_dwordx4 v[74:75], v[46:49], off
	s_mov_b32 s14, s12
	s_mov_b64 s[22:23], s[18:19]
	v_cvt_pk_bf16_f32 v46, v50, v51
	v_cvt_pk_bf16_f32 v47, v52, v53
	v_cvt_pk_bf16_f32 v48, v54, v55
	v_cvt_pk_bf16_f32 v49, v56, v57
	global_store_dwordx4 v[74:75], v[46:49], off offset:256
	v_add_co_u32_e32 v52, vcc, s89, v40
	s_nop 0
	v_or_b32_e32 v46, 32, v114
	v_ashrrev_i32_e32 v47, 31, v46
	v_lshlrev_b64 v[46:47], 16, v[46:47]
	v_lshl_add_u64 v[50:51], v[116:117], 0, v[46:47]
	v_cvt_pk_bf16_f32 v46, v94, v95
	v_cvt_pk_bf16_f32 v47, v96, v97
	v_cvt_pk_bf16_f32 v48, v98, v99
	v_cvt_pk_bf16_f32 v49, v100, v101
	global_store_dwordx4 v[50:51], v[46:49], off
	v_addc_co_u32_e32 v53, vcc, 0, v41, vcc
	s_nop 0
	v_cvt_pk_bf16_f32 v46, v58, v59
	v_cvt_pk_bf16_f32 v47, v60, v61
	v_cvt_pk_bf16_f32 v48, v62, v63
	v_cvt_pk_bf16_f32 v49, v64, v65
	global_store_dwordx4 v[50:51], v[46:49], off offset:256
	s_nop 1
	v_or_b32_e32 v46, 48, v114
	v_ashrrev_i32_e32 v47, 31, v46
	v_lshlrev_b64 v[46:47], 16, v[46:47]
	v_lshl_add_u64 v[50:51], v[116:117], 0, v[46:47]
	v_cvt_pk_bf16_f32 v46, v102, v103
	v_cvt_pk_bf16_f32 v47, v104, v105
	v_cvt_pk_bf16_f32 v48, v106, v107
	v_cvt_pk_bf16_f32 v49, v108, v109
	global_store_dwordx4 v[50:51], v[46:49], off
	s_nop 1
	v_cvt_pk_bf16_f32 v46, v66, v67
	v_cvt_pk_bf16_f32 v47, v68, v69
	v_cvt_pk_bf16_f32 v48, v70, v71
	v_cvt_pk_bf16_f32 v49, v72, v73
	global_store_dwordx4 v[50:51], v[46:49], off offset:256
	v_lshl_add_u64 v[50:51], v[40:41], 0, s[20:21]
	s_mov_b64 s[20:21], 0x900000
	v_cvt_pk_bf16_f32 v46, v142, v143
	v_cvt_pk_bf16_f32 v47, v144, v145
	v_cvt_pk_bf16_f32 v48, v162, v163
	v_cvt_pk_bf16_f32 v49, v164, v165
	global_store_dwordx4 v[52:53], v[46:49], off
	v_add_co_u32_e32 v52, vcc, s11, v40
	s_nop 0
	v_cvt_pk_bf16_f32 v46, v134, v135
	v_cvt_pk_bf16_f32 v47, v136, v137
	v_cvt_pk_bf16_f32 v48, v118, v119
	v_cvt_pk_bf16_f32 v49, v120, v121
	global_store_dwordx4 v[50:51], v[46:49], off offset:256
	v_lshl_add_u64 v[50:51], v[40:41], 0, s[20:21]
	v_addc_co_u32_e32 v53, vcc, 0, v41, vcc
	v_cvt_pk_bf16_f32 v46, v166, v167
	v_cvt_pk_bf16_f32 v47, v168, v169
	v_cvt_pk_bf16_f32 v48, v170, v171
	v_cvt_pk_bf16_f32 v49, v172, v173
	s_mov_b32 s11, 0xa00000
	global_store_dwordx4 v[52:53], v[46:49], off
	s_mov_b64 s[20:21], 0xa00000
	s_nop 0
	v_cvt_pk_bf16_f32 v46, v138, v139
	v_cvt_pk_bf16_f32 v47, v140, v141
	v_cvt_pk_bf16_f32 v48, v122, v123
	v_cvt_pk_bf16_f32 v49, v124, v125
	global_store_dwordx4 v[50:51], v[46:49], off offset:256
	v_cvt_pk_bf16_f32 v30, v30, v31
	v_cvt_pk_bf16_f32 v31, v32, v33
	v_cvt_pk_bf16_f32 v32, v22, v23
	v_add_co_u32_e32 v22, vcc, s11, v40
	s_nop 0
	v_lshl_add_u64 v[46:47], v[40:41], 0, s[20:21]
	v_addc_co_u32_e32 v23, vcc, 0, v41, vcc
	s_mov_b32 s11, 0xb00000
	v_cvt_pk_bf16_f32 v33, v24, v25
	global_store_dwordx4 v[22:23], v[30:33], off
	v_cvt_pk_bf16_f32 v22, v26, v27
	v_cvt_pk_bf16_f32 v23, v28, v29
	v_cvt_pk_bf16_f32 v24, v18, v19
	v_cvt_pk_bf16_f32 v25, v20, v21
	global_store_dwordx4 v[46:47], v[22:25], off offset:256
	v_cvt_pk_bf16_f32 v14, v14, v15
	v_cvt_pk_bf16_f32 v15, v16, v17
	v_cvt_pk_bf16_f32 v16, v6, v7
	v_add_co_u32_e32 v6, vcc, s11, v40
	s_mov_b64 s[20:21], 0xb00000
	s_nop 0
	v_addc_co_u32_e32 v7, vcc, 0, v41, vcc
	v_lshl_add_u64 v[18:19], v[40:41], 0, s[20:21]
	s_andn2_b64 vcc, exec, s[4:5]
	s_mov_b64 s[20:21], s[16:17]
	v_cvt_pk_bf16_f32 v17, v8, v9
	global_store_dwordx4 v[6:7], v[14:17], off
	v_cvt_pk_bf16_f32 v6, v10, v11
	v_cvt_pk_bf16_f32 v7, v12, v13
	v_cvt_pk_bf16_f32 v8, v2, v3
	v_cvt_pk_bf16_f32 v9, v4, v5
	global_store_dwordx4 v[18:19], v[6:9], off offset:256
	s_cbranch_vccz .LBB0_592

.LBB0_1217:
	s_add_u32 s22, s20, 0x100
	s_addc_u32 s23, s21, 0
	s_add_i32 s55, 0, 0x10000
	s_cmp_eq_u32 s54, 12
	s_cselect_b32 s27, s13, s23
	s_cselect_b32 s26, s46, s22
	v_add_u32_e32 v140, s55, v143
	s_cselect_b32 s25, s11, s53
	s_cselect_b32 s24, s47, s52
	s_add_i32 s56, 0, 0x14000
	ds_read_b128 v[136:139], v140
	ds_read_b128 v[162:165], v140 offset:1024
	ds_read_b128 v[166:169], v140 offset:2048
	ds_read_b128 v[170:173], v140 offset:3072
	v_add_u32_e32 v140, s56, v143
	ds_read_b128 v[174:177], v140
	ds_read_b128 v[178:181], v140 offset:1024
	ds_read_b128 v[182:185], v140 offset:2048
	ds_read_b128 v[186:189], v140 offset:3072
	v_lshl_add_u64 v[140:141], s[20:21], 0, v[132:133]
	s_add_i32 m0, s38, 0xc000
	ds_read_b128 v[190:193], v145
	ds_read_b128 v[194:197], v145 offset:1024
	ds_read_b128 v[198:201], v145 offset:2048
	ds_read_b128 v[202:205], v145 offset:3072
	ds_read_b128 v[206:209], v145 offset:4096
	ds_read_b128 v[220:223], v145 offset:5120
	ds_read_b128 v[232:235], v145 offset:6144
	ds_read_b128 v[236:239], v145 offset:7168
	global_load_lds_dwordx4 v[140:141], off
	v_lshl_add_u64 v[140:141], s[20:21], 0, v[134:135]
	s_add_i32 m0, s38, 0xe000
	s_nop 0
	global_load_lds_dwordx4 v[140:141], off
	s_waitcnt vmcnt(8)
	s_waitcnt lgkmcnt(0)
	s_barrier
	s_setprio 1
	v_mfma_f32_16x16x32_bf16 v[126:129], v[136:139], v[190:193], v[126:129]
	v_mfma_f32_16x16x32_bf16 v[122:125], v[166:169], v[190:193], v[122:125]
	v_mfma_f32_16x16x32_bf16 v[110:113], v[136:139], v[198:201], v[110:113]
	v_mfma_f32_16x16x32_bf16 v[106:109], v[166:169], v[198:201], v[106:109]
	v_mfma_f32_16x16x32_bf16 v[94:97], v[136:139], v[206:209], v[94:97]
	v_mfma_f32_16x16x32_bf16 v[90:93], v[166:169], v[206:209], v[90:93]
	v_mfma_f32_16x16x32_bf16 v[78:81], v[136:139], v[232:235], v[78:81]
	v_mfma_f32_16x16x32_bf16 v[74:77], v[166:169], v[232:235], v[74:77]
	v_mfma_f32_16x16x32_bf16 v[126:129], v[162:165], v[194:197], v[126:129]
	v_mfma_f32_16x16x32_bf16 v[122:125], v[170:173], v[194:197], v[122:125]
	v_mfma_f32_16x16x32_bf16 v[110:113], v[162:165], v[202:205], v[110:113]
	v_mfma_f32_16x16x32_bf16 v[106:109], v[170:173], v[202:205], v[106:109]
	v_mfma_f32_16x16x32_bf16 v[94:97], v[162:165], v[220:223], v[94:97]
	v_mfma_f32_16x16x32_bf16 v[90:93], v[170:173], v[220:223], v[90:93]
	v_mfma_f32_16x16x32_bf16 v[78:81], v[162:165], v[236:239], v[78:81]
	v_mfma_f32_16x16x32_bf16 v[74:77], v[170:173], v[236:239], v[74:77]
	v_mfma_f32_16x16x32_bf16 v[118:121], v[174:177], v[190:193], v[118:121]
	v_mfma_f32_16x16x32_bf16 v[114:117], v[182:185], v[190:193], v[114:117]
	v_mfma_f32_16x16x32_bf16 v[102:105], v[174:177], v[198:201], v[102:105]
	v_mfma_f32_16x16x32_bf16 v[98:101], v[182:185], v[198:201], v[98:101]
	v_mfma_f32_16x16x32_bf16 v[86:89], v[174:177], v[206:209], v[86:89]
	v_mfma_f32_16x16x32_bf16 v[82:85], v[182:185], v[206:209], v[82:85]
	v_mfma_f32_16x16x32_bf16 v[70:73], v[174:177], v[232:235], v[70:73]
	v_mfma_f32_16x16x32_bf16 v[66:69], v[182:185], v[232:235], v[66:69]
	v_mfma_f32_16x16x32_bf16 v[118:121], v[178:181], v[194:197], v[118:121]
	v_mfma_f32_16x16x32_bf16 v[114:117], v[186:189], v[194:197], v[114:117]
	v_mfma_f32_16x16x32_bf16 v[102:105], v[178:181], v[202:205], v[102:105]
	v_mfma_f32_16x16x32_bf16 v[98:101], v[186:189], v[202:205], v[98:101]
	v_mfma_f32_16x16x32_bf16 v[86:89], v[178:181], v[220:223], v[86:89]
	v_mfma_f32_16x16x32_bf16 v[82:85], v[186:189], v[220:223], v[82:85]
	v_mfma_f32_16x16x32_bf16 v[70:73], v[178:181], v[236:239], v[70:73]
	v_mfma_f32_16x16x32_bf16 v[66:69], v[186:189], v[236:239], v[66:69]
	s_setprio 0
	s_barrier
	s_add_i32 s20, s55, s37
	v_lshl_add_u64 v[140:141], s[24:25], 0, v[0:1]
	s_mov_b32 m0, s20
	ds_read_b128 v[190:193], v145 offset:16384
	ds_read_b128 v[194:197], v145 offset:17408
	ds_read_b128 v[198:201], v145 offset:18432
	ds_read_b128 v[202:205], v145 offset:19456
	ds_read_b128 v[206:209], v145 offset:20480
	ds_read_b128 v[220:223], v145 offset:21504
	ds_read_b128 v[232:235], v145 offset:22528
	ds_read_b128 v[236:239], v145 offset:23552
	global_load_lds_dwordx4 v[140:141], off
	s_add_i32 m0, s20, 0x2000
	s_add_u32 s20, s24, 0x40000
	v_lshl_add_u64 v[210:211], s[24:25], 0, v[130:131]
	s_addc_u32 s21, s25, 0
	s_add_i32 s55, s56, s37
	global_load_lds_dwordx4 v[210:211], off
	v_lshl_add_u64 v[240:241], s[20:21], 0, v[0:1]
	s_mov_b32 m0, s55
	v_lshl_add_u64 v[242:243], s[26:27], 0, v[130:131]
	global_load_lds_dwordx4 v[240:241], off
	v_lshl_add_u64 v[240:241], s[20:21], 0, v[130:131]
	s_add_i32 m0, s55, 0x2000
	s_nop 0
	global_load_lds_dwordx4 v[240:241], off
	v_lshl_add_u64 v[240:241], s[26:27], 0, v[0:1]
	s_mov_b32 m0, s38
	s_nop 0
	global_load_lds_dwordx4 v[240:241], off
	s_mov_b32 m0, s39
	s_nop 0
	global_load_lds_dwordx4 v[242:243], off
	s_waitcnt vmcnt(8)
	s_waitcnt lgkmcnt(0)
	s_barrier
	s_setprio 1
	v_mfma_f32_16x16x32_bf16 v[62:65], v[136:139], v[190:193], v[62:65]
	v_mfma_f32_16x16x32_bf16 v[58:61], v[166:169], v[190:193], v[58:61]
	v_mfma_f32_16x16x32_bf16 v[46:49], v[136:139], v[198:201], v[46:49]
	v_mfma_f32_16x16x32_bf16 v[42:45], v[166:169], v[198:201], v[42:45]
	v_mfma_f32_16x16x32_bf16 v[30:33], v[136:139], v[206:209], v[30:33]
	v_mfma_f32_16x16x32_bf16 v[26:29], v[166:169], v[206:209], v[26:29]
	v_mfma_f32_16x16x32_bf16 v[14:17], v[136:139], v[232:235], v[14:17]
	v_mfma_f32_16x16x32_bf16 v[10:13], v[166:169], v[232:235], v[10:13]
	v_mfma_f32_16x16x32_bf16 v[62:65], v[162:165], v[194:197], v[62:65]
	v_mfma_f32_16x16x32_bf16 v[58:61], v[170:173], v[194:197], v[58:61]
	v_mfma_f32_16x16x32_bf16 v[46:49], v[162:165], v[202:205], v[46:49]
	v_mfma_f32_16x16x32_bf16 v[42:45], v[170:173], v[202:205], v[42:45]
	v_mfma_f32_16x16x32_bf16 v[30:33], v[162:165], v[220:223], v[30:33]
	v_mfma_f32_16x16x32_bf16 v[26:29], v[170:173], v[220:223], v[26:29]
	v_mfma_f32_16x16x32_bf16 v[14:17], v[162:165], v[236:239], v[14:17]
	v_mfma_f32_16x16x32_bf16 v[10:13], v[170:173], v[236:239], v[10:13]
	v_mfma_f32_16x16x32_bf16 v[54:57], v[174:177], v[190:193], v[54:57]
	v_mfma_f32_16x16x32_bf16 v[50:53], v[182:185], v[190:193], v[50:53]
	v_mfma_f32_16x16x32_bf16 v[38:41], v[174:177], v[198:201], v[38:41]
	v_mfma_f32_16x16x32_bf16 v[34:37], v[182:185], v[198:201], v[34:37]
	v_mfma_f32_16x16x32_bf16 v[22:25], v[174:177], v[206:209], v[22:25]
	v_mfma_f32_16x16x32_bf16 v[18:21], v[182:185], v[206:209], v[18:21]
	v_mfma_f32_16x16x32_bf16 v[6:9], v[174:177], v[232:235], v[6:9]
	v_mfma_f32_16x16x32_bf16 v[2:5], v[182:185], v[232:235], v[2:5]
	v_mfma_f32_16x16x32_bf16 v[54:57], v[178:181], v[194:197], v[54:57]
	v_mfma_f32_16x16x32_bf16 v[50:53], v[186:189], v[194:197], v[50:53]
	v_mfma_f32_16x16x32_bf16 v[38:41], v[178:181], v[202:205], v[38:41]
	v_mfma_f32_16x16x32_bf16 v[34:37], v[186:189], v[202:205], v[34:37]
	v_mfma_f32_16x16x32_bf16 v[22:25], v[178:181], v[220:223], v[22:25]
	v_mfma_f32_16x16x32_bf16 v[18:21], v[186:189], v[220:223], v[18:21]
	v_mfma_f32_16x16x32_bf16 v[6:9], v[178:181], v[236:239], v[6:9]
	v_mfma_f32_16x16x32_bf16 v[2:5], v[186:189], v[236:239], v[2:5]
	s_setprio 0
	s_barrier
	s_add_i32 s55, 0, 0x18000
	v_add_u32_e32 v146, s55, v143
	s_add_i32 s56, 0, 0x1c000
	ds_read_b128 v[136:139], v146
	ds_read_b128 v[162:165], v146 offset:1024
	ds_read_b128 v[166:169], v146 offset:2048
	ds_read_b128 v[170:173], v146 offset:3072
	v_add_u32_e32 v146, s56, v143
	ds_read_b128 v[174:177], v146
	ds_read_b128 v[178:181], v146 offset:1024
	ds_read_b128 v[182:185], v146 offset:2048
	ds_read_b128 v[186:189], v146 offset:3072
	s_add_u32 s20, s26, 0x40000
	s_addc_u32 s21, s27, 0
	s_mov_b32 m0, s40
	v_lshl_add_u64 v[244:245], s[20:21], 0, v[0:1]
	ds_read_b128 v[190:193], v145 offset:32768
	ds_read_b128 v[194:197], v145 offset:33792
	ds_read_b128 v[198:201], v145 offset:34816
	ds_read_b128 v[202:205], v145 offset:35840
	ds_read_b128 v[206:209], v145 offset:36864
	ds_read_b128 v[220:223], v145 offset:37888
	ds_read_b128 v[232:235], v145 offset:38912
	ds_read_b128 v[236:239], v145 offset:39936
	global_load_lds_dwordx4 v[244:245], off
	v_lshl_add_u64 v[244:245], s[20:21], 0, v[130:131]
	s_mov_b32 m0, s41
	s_nop 0
	global_load_lds_dwordx4 v[244:245], off
	s_waitcnt vmcnt(8)
	s_waitcnt lgkmcnt(0)
	s_barrier
	s_setprio 1
	v_mfma_f32_16x16x32_bf16 v[126:129], v[136:139], v[190:193], v[126:129]
	v_mfma_f32_16x16x32_bf16 v[122:125], v[166:169], v[190:193], v[122:125]
	v_mfma_f32_16x16x32_bf16 v[110:113], v[136:139], v[198:201], v[110:113]
	v_mfma_f32_16x16x32_bf16 v[106:109], v[166:169], v[198:201], v[106:109]
	v_mfma_f32_16x16x32_bf16 v[94:97], v[136:139], v[206:209], v[94:97]
	v_mfma_f32_16x16x32_bf16 v[90:93], v[166:169], v[206:209], v[90:93]
	v_mfma_f32_16x16x32_bf16 v[78:81], v[136:139], v[232:235], v[78:81]
	v_mfma_f32_16x16x32_bf16 v[74:77], v[166:169], v[232:235], v[74:77]
	v_mfma_f32_16x16x32_bf16 v[126:129], v[162:165], v[194:197], v[126:129]
	v_mfma_f32_16x16x32_bf16 v[122:125], v[170:173], v[194:197], v[122:125]
	v_mfma_f32_16x16x32_bf16 v[110:113], v[162:165], v[202:205], v[110:113]
	v_mfma_f32_16x16x32_bf16 v[106:109], v[170:173], v[202:205], v[106:109]
	v_mfma_f32_16x16x32_bf16 v[94:97], v[162:165], v[220:223], v[94:97]
	v_mfma_f32_16x16x32_bf16 v[90:93], v[170:173], v[220:223], v[90:93]
	v_mfma_f32_16x16x32_bf16 v[78:81], v[162:165], v[236:239], v[78:81]
	v_mfma_f32_16x16x32_bf16 v[74:77], v[170:173], v[236:239], v[74:77]
	v_mfma_f32_16x16x32_bf16 v[118:121], v[174:177], v[190:193], v[118:121]
	v_mfma_f32_16x16x32_bf16 v[114:117], v[182:185], v[190:193], v[114:117]
	v_mfma_f32_16x16x32_bf16 v[102:105], v[174:177], v[198:201], v[102:105]
	v_mfma_f32_16x16x32_bf16 v[98:101], v[182:185], v[198:201], v[98:101]
	v_mfma_f32_16x16x32_bf16 v[86:89], v[174:177], v[206:209], v[86:89]
	v_mfma_f32_16x16x32_bf16 v[82:85], v[182:185], v[206:209], v[82:85]
	v_mfma_f32_16x16x32_bf16 v[70:73], v[174:177], v[232:235], v[70:73]
	v_mfma_f32_16x16x32_bf16 v[66:69], v[182:185], v[232:235], v[66:69]
	v_mfma_f32_16x16x32_bf16 v[118:121], v[178:181], v[194:197], v[118:121]
	v_mfma_f32_16x16x32_bf16 v[114:117], v[186:189], v[194:197], v[114:117]
	v_mfma_f32_16x16x32_bf16 v[102:105], v[178:181], v[202:205], v[102:105]
	v_mfma_f32_16x16x32_bf16 v[98:101], v[186:189], v[202:205], v[98:101]
	v_mfma_f32_16x16x32_bf16 v[86:89], v[178:181], v[220:223], v[86:89]
	v_mfma_f32_16x16x32_bf16 v[82:85], v[186:189], v[220:223], v[82:85]
	v_mfma_f32_16x16x32_bf16 v[70:73], v[178:181], v[236:239], v[70:73]
	v_mfma_f32_16x16x32_bf16 v[66:69], v[186:189], v[236:239], v[66:69]
	s_setprio 0
	s_barrier
	s_add_i32 s20, s55, s37
	v_lshl_add_u64 v[140:141], v[140:141], 0, s[90:91]
	s_mov_b32 m0, s20
	ds_read_b128 v[190:193], v145 offset:49152
	ds_read_b128 v[194:197], v145 offset:50176
	ds_read_b128 v[198:201], v145 offset:51200
	ds_read_b128 v[202:205], v145 offset:52224
	ds_read_b128 v[206:209], v145 offset:53248
	ds_read_b128 v[220:223], v145 offset:54272
	ds_read_b128 v[232:235], v145 offset:55296
	ds_read_b128 v[236:239], v145 offset:56320
	global_load_lds_dwordx4 v[140:141], off
	s_add_i32 m0, s20, 0x2000
	s_add_u32 s20, s24, 0x40080
	v_lshl_add_u64 v[140:141], v[210:211], 0, s[90:91]
	s_addc_u32 s21, s25, 0
	s_add_i32 s24, s56, s37
	global_load_lds_dwordx4 v[140:141], off
	v_lshl_add_u64 v[140:141], s[20:21], 0, v[0:1]
	s_mov_b32 m0, s24
	s_nop 0
	global_load_lds_dwordx4 v[140:141], off
	v_lshl_add_u64 v[140:141], s[20:21], 0, v[130:131]
	s_add_i32 m0, s24, 0x2000
	s_nop 0
	global_load_lds_dwordx4 v[140:141], off
	v_lshl_add_u64 v[140:141], v[240:241], 0, s[90:91]
	s_mov_b32 m0, s42
	s_nop 0
	global_load_lds_dwordx4 v[140:141], off
	v_lshl_add_u64 v[140:141], v[242:243], 0, s[90:91]
	s_mov_b32 m0, s43
	s_nop 0
	global_load_lds_dwordx4 v[140:141], off
	s_waitcnt vmcnt(8)
	s_waitcnt lgkmcnt(0)
	s_barrier
	s_setprio 1
	v_mfma_f32_16x16x32_bf16 v[62:65], v[136:139], v[190:193], v[62:65]
	v_mfma_f32_16x16x32_bf16 v[58:61], v[166:169], v[190:193], v[58:61]
	v_mfma_f32_16x16x32_bf16 v[46:49], v[136:139], v[198:201], v[46:49]
	v_mfma_f32_16x16x32_bf16 v[42:45], v[166:169], v[198:201], v[42:45]
	v_mfma_f32_16x16x32_bf16 v[30:33], v[136:139], v[206:209], v[30:33]
	v_mfma_f32_16x16x32_bf16 v[26:29], v[166:169], v[206:209], v[26:29]
	v_mfma_f32_16x16x32_bf16 v[14:17], v[136:139], v[232:235], v[14:17]
	v_mfma_f32_16x16x32_bf16 v[10:13], v[166:169], v[232:235], v[10:13]
	v_mfma_f32_16x16x32_bf16 v[62:65], v[162:165], v[194:197], v[62:65]
	v_mfma_f32_16x16x32_bf16 v[58:61], v[170:173], v[194:197], v[58:61]
	v_mfma_f32_16x16x32_bf16 v[46:49], v[162:165], v[202:205], v[46:49]
	v_mfma_f32_16x16x32_bf16 v[42:45], v[170:173], v[202:205], v[42:45]
	v_mfma_f32_16x16x32_bf16 v[30:33], v[162:165], v[220:223], v[30:33]
	v_mfma_f32_16x16x32_bf16 v[26:29], v[170:173], v[220:223], v[26:29]
	v_mfma_f32_16x16x32_bf16 v[14:17], v[162:165], v[236:239], v[14:17]
	v_mfma_f32_16x16x32_bf16 v[10:13], v[170:173], v[236:239], v[10:13]
	v_mfma_f32_16x16x32_bf16 v[54:57], v[174:177], v[190:193], v[54:57]
	v_mfma_f32_16x16x32_bf16 v[50:53], v[182:185], v[190:193], v[50:53]
	v_mfma_f32_16x16x32_bf16 v[38:41], v[174:177], v[198:201], v[38:41]
	v_mfma_f32_16x16x32_bf16 v[34:37], v[182:185], v[198:201], v[34:37]
	v_mfma_f32_16x16x32_bf16 v[22:25], v[174:177], v[206:209], v[22:25]
	v_mfma_f32_16x16x32_bf16 v[18:21], v[182:185], v[206:209], v[18:21]
	v_mfma_f32_16x16x32_bf16 v[6:9], v[174:177], v[232:235], v[6:9]
	v_mfma_f32_16x16x32_bf16 v[2:5], v[182:185], v[232:235], v[2:5]
	v_mfma_f32_16x16x32_bf16 v[54:57], v[178:181], v[194:197], v[54:57]
	v_mfma_f32_16x16x32_bf16 v[50:53], v[186:189], v[194:197], v[50:53]
	v_mfma_f32_16x16x32_bf16 v[38:41], v[178:181], v[202:205], v[38:41]
	v_mfma_f32_16x16x32_bf16 v[34:37], v[186:189], v[202:205], v[34:37]
	v_mfma_f32_16x16x32_bf16 v[22:25], v[178:181], v[220:223], v[22:25]
	v_mfma_f32_16x16x32_bf16 v[18:21], v[186:189], v[220:223], v[18:21]
	v_mfma_f32_16x16x32_bf16 v[6:9], v[178:181], v[236:239], v[6:9]
	v_mfma_f32_16x16x32_bf16 v[2:5], v[186:189], v[236:239], v[2:5]
	s_setprio 0
	s_barrier
	s_add_i32 s54, s54, 2
	s_add_u32 s52, s52, 0x100
	s_addc_u32 s53, s53, 0
	s_cmp_gt_u32 s54, 13
	s_mov_b64 s[20:21], s[22:23]
	s_cbranch_scc0 .LBB0_1217
	s_and_b64 vcc, exec, s[8:9]
	s_cbranch_vccz .LBB0_1220
	s_barrier
